# GLA gate operands (la) parked in LDS by phase a and re-used by phase c instead of recomputed
# speedup vs baseline: 1.0323x; 1.0093x over previous
; template <int MODE> __device__ void mixer_gla(const Params& p, int l, int n, LAS unsigned char* lds) {
;     ...
;         bf16x8 laop[4][2]; float tot[4];
;         {
;             bf16x8 lrf[4], gwf[4]; float bgv[4];
; #pragma unroll
;             for (int tt = 0; tt < 4; ++tt) { lrf[tt] = (bf16x8){0, 0, 0, 0, 0, 0, 0, 0}; if (q < 2) lrf[tt] = *(const bf16x8*)(proj + (size_t)(t0 + 16 * tt + c) * DINP + 2560 + dir * 16 + 8 * q); }
; #pragma unroll
;             for (int ef = 0; ef < 4; ++ef) { gwf[ef] = *(const bf16x8*)(GW + (size_t)(dir * 256 + 64 * h + SIGC(ef, c)) * 32 + 8 * q); bgv[ef] = p.in[13][(size_t)(l * 2 + dir) * 256 + 64 * h + SIGC(ef, c)]; }
; #pragma unroll
;             for (int ef = 0; ef < 4; ++ef) { tot[ef] = 0.f;
; #pragma unroll
;                 for (int ks = 0; ks < 2; ++ks) { f32x4 la2[2];
; #pragma unroll
;                     for (int t2 = 0; t2 < 2; ++t2) { const f32x4 z = mfma16(lrf[2 * ks + t2], gwf[ef], zero4);
; #pragma unroll
;                         for (int r = 0; r < 4; ++r) { const float zz = z[r] + bgv[ef]; const float la = (fminf(zz, 0.f) - __logf(1.0f + __expf(-fabsf(zz)))) * (1.0f / 16.0f); la2[t2][r] = la; tot[ef] += la; } }
;                     laop[ef][ks] = pack8(la2[0], la2[1]); __builtin_amdgcn_sched_barrier(0); } }
;         }
;         if (MODE == 1) {
;             bf16x8 QEop[4][2], KEop[4][2];
;             bf16x8 qn[4][2], kn1[4][2];
; #pragma unroll
;             for (int tj = 0; tj < 4; ++tj)
; #pragma unroll
;                 for (int ks = 0; ks < 2; ++ks) { const bf16_t* rp = proj + (size_t)(t0 + 16 * tj + c) * DINP + 64 * h + 32 * ks + 8 * q; qn[tj][ks] = *(const bf16x8*)(rp + 1024); kn1[tj][ks] = *(const bf16x8*)(rp + 1280); }
;             __builtin_amdgcn_sched_barrier(0);
; #pragma unroll
;             for (int tj = 0; tj < 4; ++tj) {
;                 const int t = 16 * tj + c;
;                 bf16x8 mk[2];
; #pragma unroll
;                 for (int ks = 0; ks < 2; ++ks)
; #pragma unroll
;                     for (int jj = 0; jj < 8; ++jj) { const int sidx = SLOT(ks, q, jj); const bool on = dir == 0 ? sidx <= t : sidx >= t; mk[ks][jj] = on ? (short)0x3F80 : (short)0; }
; #pragma unroll
;                 for (int ks2 = 0; ks2 < 2; ++ks2) { f32x4 qe2[2], ke2[2];
; #pragma unroll
;                     for (int e2 = 0; e2 < 2; ++e2) { const int ef = 2 * ks2 + e2;
.LBB0_151:
	s_or_b64 exec, exec, s[0:1]
	s_lshl_b32 s34, s4, 8
	s_xor_b64 s[30:31], s[26:27], -1
	v_lshrrev_b32_e32 v116, 7, v245
	v_and_b32_e32 v117, 63, v245
	v_lshlrev_b32_e32 v116, 14, v116
	v_lshl_add_u32 v116, v117, 4, v116
	v_lshl_add_u32 v116, s4, 13, v116
	s_waitcnt vmcnt(0)
	ds_read_b128 v[76:79], v116
	ds_read_b128 v[84:87], v116 offset:1024
	ds_read_b128 v[96:99], v116 offset:2048
	ds_read_b128 v[100:103], v116 offset:3072
	ds_read_b128 v[104:107], v116 offset:4096
	ds_read_b128 v[92:95], v116 offset:5120
	ds_read_b128 v[80:83], v116 offset:6144
	ds_read_b128 v[112:115], v116 offset:7168
	s_waitcnt lgkmcnt(0)
	global_load_dwordx4 v[64:67], v[212:213], off offset:2048
	global_load_dwordx4 v[120:123], v[212:213], off offset:2112
	global_load_dwordx4 v[72:75], v[212:213], off offset:2560
	global_load_dwordx4 v[68:71], v[212:213], off offset:2624
	global_load_dwordx4 v[136:139], v[214:215], off offset:2048
	global_load_dwordx4 v[156:159], v[214:215], off offset:2112
	global_load_dwordx4 v[116:119], v[214:215], off offset:2560
	global_load_dwordx4 v[132:135], v[214:215], off offset:2624
	global_load_dwordx4 v[164:167], v[216:217], off offset:2048
	global_load_dwordx4 v[144:147], v[216:217], off offset:2112
	global_load_dwordx4 v[160:163], v[216:217], off offset:2560
	global_load_dwordx4 v[140:143], v[216:217], off offset:2624
	global_load_dwordx4 v[128:131], v[218:219], off offset:2048
	global_load_dwordx4 v[108:111], v[218:219], off offset:2112
	global_load_dwordx4 v[124:127], v[218:219], off offset:2560
	global_load_dwordx4 v[88:91], v[218:219], off offset:2624
	v_readlane_b32 s0, v255, 22
	v_readlane_b32 s1, v255, 23
	v_cndmask_b32_e64 v149, 0, 1, s[28:29]
	v_cndmask_b32_e64 v150, 0, 1, s[40:41]
	v_cndmask_b32_e64 v148, 0, 1, s[0:1]
	v_cndmask_b32_e64 v148, v149, v148, s[26:27]
	v_and_b32_e32 v148, 1, v148
	v_cmp_eq_u32_e64 s[16:17], 1, v148
	v_cndmask_b32_e64 v148, 0, 1, s[44:45]
	v_cndmask_b32_e64 v149, 0, 1, s[46:47]
	v_cndmask_b32_e64 v148, v149, v148, s[26:27]
	v_cndmask_b32_e64 v149, 0, 1, s[48:49]
	v_cndmask_b32_e64 v149, v150, v149, s[26:27]
	v_cndmask_b32_e64 v150, 0, 1, s[52:53]
	v_cndmask_b32_e64 v151, 0, 1, s[54:55]
	v_cndmask_b32_e64 v150, v151, v150, s[26:27]
	v_and_b32_e32 v148, 1, v148
	v_and_b32_e32 v149, 1, v149
	v_and_b32_e32 v150, 1, v150
	s_and_b64 s[0:1], s[26:27], exec
	v_cmp_eq_u32_e64 s[92:93], 1, v148
	v_cmp_eq_u32_e64 s[94:95], 1, v149
	v_cmp_eq_u32_e64 s[96:97], 1, v150
	s_cselect_b32 s0, 0, 0x3f80
	v_cndmask_b32_e64 v176, 0, v229, s[16:17]
	v_cndmask_b32_e64 v148, 0, v229, s[92:93]
	v_cndmask_b32_e64 v149, 0, v229, s[94:95]
	v_cndmask_b32_e64 v150, 0, v229, s[96:97]
	s_pack_ll_b32_b16 s4, s0, s0
	v_perm_b32 v148, v148, v176, s3
	v_perm_b32 v149, v150, v149, s3
	v_mov_b32_e32 v150, s4
	v_mov_b32_e32 v151, s4
	s_mov_b32 s6, s4
	s_mov_b32 s7, s4
	v_mfma_f32_16x16x32_bf16 v[152:155], v[76:79], v[148:151], 0
	s_mov_b32 s5, s4
	v_mov_b64_e32 v[170:171], s[6:7]
	v_mov_b64_e32 v[168:169], s[4:5]
	s_waitcnt vmcnt(15)
	v_and_b32_e32 v175, 0xffff0000, v64
	v_lshlrev_b32_e32 v174, 16, v64
	v_mfma_f32_16x16x32_bf16 v[152:155], v[84:87], v[168:171], v[152:155]
	v_mul_f32_e64 v174, v174, s24
	v_mul_f32_e64 v175, v175, s24
	v_and_b32_e32 v179, 0xffff0000, v65
	v_lshlrev_b32_e32 v178, 16, v65
	v_pk_mul_f32 v[178:179], v[178:179], s[24:25] op_sel_hi:[1,0]
	s_waitcnt vmcnt(13)
	v_and_b32_e32 v181, 0xffff0000, v73
	s_nop 0
	v_mul_f32_e32 v172, 0x3fb8aa3b, v152
	v_mul_f32_e32 v173, 0x3fb8aa3b, v153
	v_exp_f32_e32 v172, v172
	v_mul_f32_e32 v152, 0xbfb8aa3b, v152
	v_exp_f32_e32 v173, v173
	v_mul_f32_e32 v64, 0xbfb8aa3b, v153
	v_exp_f32_e32 v152, v152
	v_exp_f32_e32 v153, v64
	v_pk_mul_f32 v[172:173], v[174:175], v[172:173]
	v_and_b32_e32 v175, 0xffff0000, v72
	v_lshlrev_b32_e32 v174, 16, v72
	v_mul_f32_e32 v64, 0x3fb8aa3b, v154
	v_mul_f32_e32 v72, 0x3fb8aa3b, v155
	v_pk_mul_f32 v[174:175], v[152:153], v[174:175]
	v_exp_f32_e32 v152, v64
	v_exp_f32_e32 v153, v72
	v_mul_f32_e32 v64, 0xbfb8aa3b, v154
	v_mul_f32_e32 v65, 0xbfb8aa3b, v155
	v_exp_f32_e32 v64, v64
	v_pk_mul_f32 v[178:179], v[178:179], v[152:153]
	v_mfma_f32_16x16x32_bf16 v[152:155], v[96:99], v[148:151], 0
	v_exp_f32_e32 v65, v65
	v_lshlrev_b32_e32 v180, 16, v73
	v_and_b32_e32 v189, 0xffff0000, v66
	v_mfma_f32_16x16x32_bf16 v[152:155], v[100:103], v[168:171], v[152:155]
	v_mul_f32_e64 v180, v64, v180
	v_mul_f32_e64 v181, v65, v181
	v_lshlrev_b32_e32 v188, 16, v66
	v_pk_mul_f32 v[188:189], v[188:189], s[24:25] op_sel_hi:[1,0]
	s_nop 3
	v_mul_f32_e32 v65, 0xbfb8aa3b, v152
	v_mul_f32_e32 v64, 0x3fb8aa3b, v152
	v_exp_f32_e32 v72, v65
	v_mul_f32_e32 v65, 0x3fb8aa3b, v153
	v_exp_f32_e32 v64, v64
	v_exp_f32_e32 v65, v65
	v_mul_f32_e32 v66, 0xbfb8aa3b, v153
	v_exp_f32_e32 v73, v66
	v_pk_mul_f32 v[152:153], v[188:189], v[64:65]
	v_and_b32_e32 v65, 0xffff0000, v74
	v_lshlrev_b32_e32 v64, 16, v74
	v_pk_mul_f32 v[188:189], v[72:73], v[64:65]
	v_mul_f32_e32 v65, 0xbfb8aa3b, v154
	v_mul_f32_e32 v64, 0x3fb8aa3b, v154
	v_exp_f32_e32 v66, v65
	v_mul_f32_e32 v65, 0x3fb8aa3b, v155
	v_exp_f32_e32 v64, v64
	v_exp_f32_e32 v65, v65
	v_and_b32_e32 v73, 0xffff0000, v67
	v_lshlrev_b32_e32 v72, 16, v67
	v_mul_f32_e32 v67, 0xbfb8aa3b, v155
	v_exp_f32_e32 v67, v67
	v_pk_mul_f32 v[72:73], v[72:73], s[24:25] op_sel_hi:[1,0]
	v_cvt_pk_bf16_f32 v74, v188, v189
	v_pk_mul_f32 v[72:73], v[72:73], v[64:65]
	v_and_b32_e32 v65, 0xffff0000, v75
	v_lshlrev_b32_e32 v64, 16, v75
	v_pk_mul_f32 v[190:191], v[66:67], v[64:65]
	v_cvt_pk_bf16_f32 v66, v152, v153
	v_mfma_f32_16x16x32_bf16 v[152:155], v[104:107], v[148:151], 0
	v_cvt_pk_bf16_f32 v64, v172, v173
	v_cvt_pk_bf16_f32 v67, v72, v73
	v_cvt_pk_bf16_f32 v72, v174, v175
	v_mfma_f32_16x16x32_bf16 v[152:155], v[92:95], v[168:171], v[152:155]
	v_and_b32_e32 v175, 0xffff0000, v120
	v_lshlrev_b32_e32 v174, 16, v120
	v_pk_mul_f32 v[174:175], v[174:175], s[24:25] op_sel_hi:[1,0]
	v_cvt_pk_bf16_f32 v65, v178, v179
	v_and_b32_e32 v179, 0xffff0000, v121
	s_nop 2
	v_mul_f32_e32 v172, 0x3fb8aa3b, v152
	v_mul_f32_e32 v173, 0x3fb8aa3b, v153
	v_exp_f32_e32 v172, v172
	v_mul_f32_e32 v152, 0xbfb8aa3b, v152
	v_exp_f32_e32 v173, v173
	v_mul_f32_e32 v120, 0xbfb8aa3b, v153
	v_exp_f32_e32 v152, v152
	v_exp_f32_e32 v153, v120
	v_pk_mul_f32 v[172:173], v[174:175], v[172:173]
	s_waitcnt vmcnt(12)
; __device__ __forceinline__ float bf2f(bf16_t b) { return __uint_as_float(((unsigned)b) << 16); }
; __device__ __forceinline__ f32x4 mfma16(bf16x8 a, bf16x8 b, f32x4 c) { return __builtin_amdgcn_mfma_f32_16x16x32_bf16(a, b, c, 0, 0, 0); }
; template <int MODE> __device__ void mixer_gla(const Params& p, int l, int n, LAS unsigned char* lds) {
;     ...
;             for (int tj = 0; tj < 4; ++tj) {
;                 const int t = 16 * tj + c;
;                 bf16x8 mk[2];
; #pragma unroll
;                 for (int ks = 0; ks < 2; ++ks)
; #pragma unroll
;                     for (int jj = 0; jj < 8; ++jj) { const int sidx = SLOT(ks, q, jj); const bool on = dir == 0 ? sidx <= t : sidx >= t; mk[ks][jj] = on ? (short)0x3F80 : (short)0; }
; #pragma unroll
;                 for (int ks2 = 0; ks2 < 2; ++ks2) { f32x4 qe2[2], ke2[2];
; #pragma unroll
;                     for (int e2 = 0; e2 < 2; ++e2) { const int ef = 2 * ks2 + e2;
;                         f32x4 b = mfma16(laop[ef][0], mk[0], zero4); b = mfma16(laop[ef][1], mk[1], b);
; #pragma unroll
;                         for (int r = 0; r < 4; ++r) { qe2[e2][r] = bf2f((bf16_t)qn[tj][ks2][4 * e2 + r]) * 0.125f * __expf(b[r]); ke2[e2][r] = bf2f((bf16_t)kn1[tj][ks2][4 * e2 + r]) * __expf(-b[r]); } }
;                     QEop[tj][ks2] = pack8(qe2[0], qe2[1]); KEop[tj][ks2] = pack8(ke2[0], ke2[1]); }
	v_and_b32_e32 v175, 0xffff0000, v68
	v_lshlrev_b32_e32 v174, 16, v68
	v_mul_f32_e32 v68, 0x3fb8aa3b, v154
	v_pk_mul_f32 v[174:175], v[152:153], v[174:175]
	v_exp_f32_e32 v152, v68
	v_mul_f32_e32 v68, 0xbfb8aa3b, v154
	v_exp_f32_e32 v120, v68
	v_mul_f32_e32 v68, 0x3fb8aa3b, v155
	v_exp_f32_e32 v153, v68
	v_lshlrev_b32_e32 v178, 16, v121
	v_pk_mul_f32 v[178:179], v[178:179], s[24:25] op_sel_hi:[1,0]
	v_mul_f32_e32 v68, 0xbfb8aa3b, v155
	v_pk_mul_f32 v[178:179], v[178:179], v[152:153]
	v_mfma_f32_16x16x32_bf16 v[152:155], v[80:83], v[148:151], 0
	v_exp_f32_e32 v121, v68
	v_and_b32_e32 v149, 0xffff0000, v69
	v_lshlrev_b32_e32 v148, 16, v69
	v_mfma_f32_16x16x32_bf16 v[152:155], v[112:115], v[168:171], v[152:155]
	v_mul_f32_e64 v148, v120, v148
	v_mul_f32_e64 v149, v121, v149
	v_cvt_pk_bf16_f32 v73, v180, v181
	v_and_b32_e32 v181, 0xffff0000, v122
	v_lshlrev_b32_e32 v180, 16, v122
	v_pk_mul_f32 v[180:181], v[180:181], s[24:25] op_sel_hi:[1,0]
	s_nop 1
	v_mul_f32_e32 v69, 0xbfb8aa3b, v152
	v_mul_f32_e32 v68, 0x3fb8aa3b, v152
	v_exp_f32_e32 v120, v69
	v_mul_f32_e32 v69, 0x3fb8aa3b, v153
	v_exp_f32_e32 v68, v68
	v_exp_f32_e32 v69, v69
	v_mul_f32_e32 v121, 0xbfb8aa3b, v153
	v_exp_f32_e32 v121, v121
	v_and_b32_e32 v189, 0xffff0000, v123
	v_pk_mul_f32 v[152:153], v[180:181], v[68:69]
	v_and_b32_e32 v69, 0xffff0000, v70
	v_lshlrev_b32_e32 v68, 16, v70
	v_pk_mul_f32 v[180:181], v[120:121], v[68:69]
	v_mul_f32_e32 v69, 0xbfb8aa3b, v154
	v_mul_f32_e32 v68, 0x3fb8aa3b, v154
	v_exp_f32_e32 v120, v69
	v_mul_f32_e32 v69, 0x3fb8aa3b, v155
	v_exp_f32_e32 v68, v68
	v_exp_f32_e32 v69, v69
	v_mul_f32_e32 v70, 0xbfb8aa3b, v155
	v_exp_f32_e32 v121, v70
	v_lshlrev_b32_e32 v188, 16, v123
	v_pk_mul_f32 v[122:123], v[188:189], s[24:25] op_sel_hi:[1,0]
	v_cvt_pk_bf16_f32 v75, v190, v191
	v_pk_mul_f32 v[122:123], v[122:123], v[68:69]
	v_and_b32_e32 v69, 0xffff0000, v71
	v_lshlrev_b32_e32 v68, 16, v71
	v_pk_mul_f32 v[154:155], v[120:121], v[68:69]
	v_cvt_pk_bf16_f32 v68, v172, v173
	v_cvt_pk_bf16_f32 v69, v178, v179
	v_cvt_pk_bf16_f32 v70, v152, v153
	v_cvt_pk_bf16_f32 v71, v122, v123
	v_cvt_pk_bf16_f32 v120, v174, v175
	v_cvt_pk_bf16_f32 v121, v148, v149
	v_cvt_pk_bf16_f32 v122, v180, v181
	v_cvt_pk_bf16_f32 v123, v154, v155
	v_cndmask_b32_e64 v148, 0, 1, s[56:57]
	v_cndmask_b32_e64 v149, 0, 1, s[58:59]
	v_cndmask_b32_e64 v148, v149, v148, s[26:27]
	v_and_b32_e32 v148, 1, v148
	v_cmp_eq_u32_e64 s[20:21], 1, v148
	v_cndmask_b32_e64 v149, 0, 1, s[62:63]
	v_cndmask_b32_e64 v151, 0, 1, s[66:67]
	v_cndmask_b32_e64 v148, 0, v229, s[20:21]
	v_perm_b32 v154, v148, v176, s3
	v_cndmask_b32_e64 v148, 0, 1, s[60:61]
	v_cndmask_b32_e64 v148, v149, v148, s[26:27]
	v_cndmask_b32_e64 v149, 0, 1, s[64:65]
	v_cndmask_b32_e64 v149, v151, v149, s[26:27]
	v_and_b32_e32 v148, 1, v148
	v_and_b32_e32 v149, 1, v149
	s_cselect_b32 s0, 0x3f80, 0
	v_cmp_eq_u32_e64 s[4:5], 1, v148
	v_cmp_eq_u32_e64 s[6:7], 1, v149
	s_pack_ll_b32_b16 s12, s0, s0
	v_cndmask_b32_e64 v148, 0, v229, s[4:5]
	v_cndmask_b32_e64 v149, 0, v229, s[6:7]
	v_perm_b32 v155, v149, v148, s3
	v_mov_b32_e32 v152, s12
	v_mov_b32_e32 v153, s12
	s_waitcnt vmcnt(11)
	v_and_b32_e32 v179, 0xffff0000, v136
	v_lshlrev_b32_e32 v178, 16, v136
	v_mfma_f32_16x16x32_bf16 v[172:175], v[76:79], v[152:155], 0
	v_mul_f32_e64 v178, v178, s24
	v_mul_f32_e64 v179, v179, s24
	v_and_b32_e32 v181, 0xffff0000, v137
	v_lshlrev_b32_e32 v180, 16, v137
	v_mfma_f32_16x16x32_bf16 v[172:175], v[84:87], v[168:171], v[172:175]
	v_mul_f32_e64 v180, v180, s24
	v_mul_f32_e64 v181, v181, s24
	s_waitcnt vmcnt(9)
	v_and_b32_e32 v189, 0xffff0000, v117
	v_lshlrev_b32_e32 v188, 16, v117
	v_and_b32_e32 v191, 0xffff0000, v138
	v_lshlrev_b32_e32 v190, 16, v138
	s_nop 0
	v_mul_f32_e32 v149, 0xbfb8aa3b, v172
	v_mul_f32_e32 v148, 0x3fb8aa3b, v172
	v_exp_f32_e32 v172, v149
	v_mul_f32_e32 v149, 0x3fb8aa3b, v173
	v_exp_f32_e32 v148, v148
	v_exp_f32_e32 v149, v149
	v_mul_f32_e32 v136, 0xbfb8aa3b, v173
	v_exp_f32_e32 v173, v136
	v_pk_mul_f32 v[190:191], v[190:191], s[24:25] op_sel_hi:[1,0]
	v_pk_mul_f32 v[148:149], v[178:179], v[148:149]
	v_and_b32_e32 v179, 0xffff0000, v116
	v_lshlrev_b32_e32 v178, 16, v116
	v_mul_f32_e32 v116, 0x3fb8aa3b, v174
	v_pk_mul_f32 v[178:179], v[172:173], v[178:179]
	v_exp_f32_e32 v172, v116
	v_mul_f32_e32 v116, 0xbfb8aa3b, v174
	v_exp_f32_e32 v136, v116
	v_mul_f32_e32 v116, 0x3fb8aa3b, v175
	v_exp_f32_e32 v173, v116
	v_mul_f32_e32 v116, 0xbfb8aa3b, v175
	v_exp_f32_e32 v137, v116
	v_and_b32_e32 v247, 0xffff0000, v139
	v_pk_mul_f32 v[180:181], v[180:181], v[172:173]
	v_mfma_f32_16x16x32_bf16 v[172:175], v[96:99], v[152:155], 0
	v_mul_f32_e64 v188, v136, v188
	v_mul_f32_e64 v189, v137, v189
	v_lshlrev_b32_e32 v246, 16, v139
	v_pk_mul_f32 v[138:139], v[246:247], s[24:25] op_sel_hi:[1,0]
	v_mfma_f32_16x16x32_bf16 v[172:175], v[100:103], v[168:171], v[172:175]
	s_nop 7
	v_mul_f32_e32 v117, 0xbfb8aa3b, v172
	v_mul_f32_e32 v116, 0x3fb8aa3b, v172
	v_exp_f32_e32 v136, v117
	v_mul_f32_e32 v117, 0x3fb8aa3b, v173
	v_exp_f32_e32 v116, v116
	v_exp_f32_e32 v117, v117
	v_mul_f32_e32 v137, 0xbfb8aa3b, v173
	v_exp_f32_e32 v137, v137
	v_pk_mul_f32 v[172:173], v[190:191], v[116:117]
	v_and_b32_e32 v117, 0xffff0000, v118
	v_lshlrev_b32_e32 v116, 16, v118
	v_pk_mul_f32 v[190:191], v[136:137], v[116:117]
	v_mul_f32_e32 v117, 0xbfb8aa3b, v174
	v_mul_f32_e32 v118, 0xbfb8aa3b, v175
	v_mul_f32_e32 v116, 0x3fb8aa3b, v174
	v_exp_f32_e32 v136, v117
	v_mul_f32_e32 v117, 0x3fb8aa3b, v175
	v_exp_f32_e32 v137, v118
	v_cvt_pk_bf16_f32 v118, v172, v173
	v_mfma_f32_16x16x32_bf16 v[172:175], v[104:107], v[152:155], 0
	v_exp_f32_e32 v116, v116
	v_exp_f32_e32 v117, v117
	v_mfma_f32_16x16x32_bf16 v[172:175], v[92:95], v[168:171], v[172:175]
	v_mul_f32_e64 v138, v138, v116
	v_mul_f32_e64 v139, v139, v117
	v_and_b32_e32 v117, 0xffff0000, v119
	v_lshlrev_b32_e32 v116, 16, v119
	v_pk_mul_f32 v[246:247], v[136:137], v[116:117]
	v_cvt_pk_bf16_f32 v116, v148, v149
	s_nop 1
	v_mul_f32_e32 v149, 0xbfb8aa3b, v172
	v_mul_f32_e32 v148, 0x3fb8aa3b, v172
	v_exp_f32_e32 v172, v149
	v_mul_f32_e32 v149, 0x3fb8aa3b, v173
	v_exp_f32_e32 v148, v148
	v_exp_f32_e32 v149, v149
	v_mul_f32_e32 v151, 0xbfb8aa3b, v173
	v_exp_f32_e32 v173, v151
	v_cvt_pk_bf16_f32 v136, v178, v179
	v_and_b32_e32 v179, 0xffff0000, v156
	v_lshlrev_b32_e32 v178, 16, v156
	v_pk_mul_f32 v[178:179], v[178:179], s[24:25] op_sel_hi:[1,0]
	v_cvt_pk_bf16_f32 v117, v180, v181
	v_pk_mul_f32 v[148:149], v[178:179], v[148:149]
	s_waitcnt vmcnt(8)
; __device__ __forceinline__ float bf2f(bf16_t b) { return __uint_as_float(((unsigned)b) << 16); }
; __device__ __forceinline__ f32x4 mfma16(bf16x8 a, bf16x8 b, f32x4 c) { return __builtin_amdgcn_mfma_f32_16x16x32_bf16(a, b, c, 0, 0, 0); }
; template <int MODE> __device__ void mixer_gla(const Params& p, int l, int n, LAS unsigned char* lds) {
;     ...
;             for (int tj = 0; tj < 4; ++tj) {
;                 const int t = 16 * tj + c;
;                 bf16x8 mk[2];
; #pragma unroll
;                 for (int ks = 0; ks < 2; ++ks)
; #pragma unroll
;                     for (int jj = 0; jj < 8; ++jj) { const int sidx = SLOT(ks, q, jj); const bool on = dir == 0 ? sidx <= t : sidx >= t; mk[ks][jj] = on ? (short)0x3F80 : (short)0; }
; #pragma unroll
;                 for (int ks2 = 0; ks2 < 2; ++ks2) { f32x4 qe2[2], ke2[2];
; #pragma unroll
;                     for (int e2 = 0; e2 < 2; ++e2) { const int ef = 2 * ks2 + e2;
;                         f32x4 b = mfma16(laop[ef][0], mk[0], zero4); b = mfma16(laop[ef][1], mk[1], b);
; #pragma unroll
;                         for (int r = 0; r < 4; ++r) { qe2[e2][r] = bf2f((bf16_t)qn[tj][ks2][4 * e2 + r]) * 0.125f * __expf(b[r]); ke2[e2][r] = bf2f((bf16_t)kn1[tj][ks2][4 * e2 + r]) * __expf(-b[r]); } }
;                     QEop[tj][ks2] = pack8(qe2[0], qe2[1]); KEop[tj][ks2] = pack8(ke2[0], ke2[1]); }
	v_and_b32_e32 v179, 0xffff0000, v132
	v_lshlrev_b32_e32 v178, 16, v132
	v_mul_f32_e32 v132, 0x3fb8aa3b, v174
	v_pk_mul_f32 v[172:173], v[172:173], v[178:179]
	v_exp_f32_e32 v178, v132
	v_mul_f32_e32 v132, 0xbfb8aa3b, v174
	v_exp_f32_e32 v174, v132
	v_mul_f32_e32 v132, 0x3fb8aa3b, v175
	v_exp_f32_e32 v179, v132
	v_and_b32_e32 v181, 0xffff0000, v157
	v_lshlrev_b32_e32 v180, 16, v157
	v_pk_mul_f32 v[156:157], v[180:181], s[24:25] op_sel_hi:[1,0]
	v_mul_f32_e32 v132, 0xbfb8aa3b, v175
	v_pk_mul_f32 v[178:179], v[156:157], v[178:179]
	v_mfma_f32_16x16x32_bf16 v[154:157], v[80:83], v[152:155], 0
	v_and_b32_e32 v181, 0xffff0000, v133
	v_lshlrev_b32_e32 v180, 16, v133
	v_exp_f32_e32 v175, v132
	v_mfma_f32_16x16x32_bf16 v[154:157], v[112:115], v[168:171], v[154:157]
	v_and_b32_e32 v169, 0xffff0000, v158
	v_lshlrev_b32_e32 v168, 16, v158
	v_pk_mul_f32 v[168:169], v[168:169], s[24:25] op_sel_hi:[1,0]
	v_and_b32_e32 v171, 0xffff0000, v159
	v_lshlrev_b32_e32 v170, 16, v159
	s_nop 2
	v_mul_f32_e32 v133, 0xbfb8aa3b, v154
	v_mul_f32_e32 v132, 0x3fb8aa3b, v154
	v_exp_f32_e32 v154, v133
	v_mul_f32_e32 v133, 0x3fb8aa3b, v155
	v_exp_f32_e32 v132, v132
	v_exp_f32_e32 v133, v133
	v_mul_f32_e32 v151, 0xbfb8aa3b, v155
	v_exp_f32_e32 v155, v151
	v_pk_mul_f32 v[158:159], v[170:171], s[24:25] op_sel_hi:[1,0]
	v_pk_mul_f32 v[168:169], v[168:169], v[132:133]
	v_and_b32_e32 v133, 0xffff0000, v134
	v_lshlrev_b32_e32 v132, 16, v134
	v_pk_mul_f32 v[154:155], v[154:155], v[132:133]
	v_mul_f32_e32 v133, 0xbfb8aa3b, v156
	v_mul_f32_e32 v132, 0x3fb8aa3b, v156
	v_exp_f32_e32 v156, v133
	v_mul_f32_e32 v133, 0x3fb8aa3b, v157
	v_exp_f32_e32 v132, v132
	v_exp_f32_e32 v133, v133
	v_mul_f32_e32 v134, 0xbfb8aa3b, v157
	v_exp_f32_e32 v157, v134
	v_pk_mul_f32 v[174:175], v[174:175], v[180:181]
	v_pk_mul_f32 v[158:159], v[158:159], v[132:133]
	v_and_b32_e32 v133, 0xffff0000, v135
	v_lshlrev_b32_e32 v132, 16, v135
	v_pk_mul_f32 v[170:171], v[156:157], v[132:133]
	v_cvt_pk_bf16_f32 v119, v138, v139
	v_cvt_pk_bf16_f32 v137, v188, v189
	v_cvt_pk_bf16_f32 v138, v190, v191
	v_cvt_pk_bf16_f32 v139, v246, v247
	v_cvt_pk_bf16_f32 v132, v148, v149
	v_cvt_pk_bf16_f32 v133, v178, v179
	v_cvt_pk_bf16_f32 v134, v168, v169
	v_cvt_pk_bf16_f32 v135, v158, v159
	v_cvt_pk_bf16_f32 v156, v172, v173
	v_cvt_pk_bf16_f32 v157, v174, v175
	v_cvt_pk_bf16_f32 v158, v154, v155
	v_cvt_pk_bf16_f32 v159, v170, v171
	v_cndmask_b32_e64 v148, 0, 1, s[68:69]
	v_cndmask_b32_e64 v149, 0, 1, s[70:71]
	v_cndmask_b32_e64 v148, v149, v148, s[26:27]
	v_cndmask_b32_e64 v149, 0, 1, s[72:73]
	v_cndmask_b32_e64 v151, 0, 1, s[74:75]
	s_mov_b32 s14, s12
	s_mov_b32 s15, s12
	v_cndmask_b32_e64 v149, v151, v149, s[26:27]
	v_cndmask_b32_e64 v151, 0, 1, s[76:77]
	v_cndmask_b32_e64 v153, 0, 1, s[78:79]
	s_mov_b32 s13, s12
	v_mov_b64_e32 v[248:249], s[14:15]
	v_cndmask_b32_e64 v151, v153, v151, s[26:27]
	v_mov_b64_e32 v[246:247], s[12:13]
	v_and_b32_e32 v148, 1, v148
	v_and_b32_e32 v149, 1, v149
	v_and_b32_e32 v151, 1, v151
	v_mfma_f32_16x16x32_bf16 v[168:171], v[76:79], v[246:249], 0
	v_cmp_eq_u32_e64 s[8:9], 1, v148
	v_cmp_eq_u32_e64 s[10:11], 1, v149
	v_cmp_eq_u32_e64 s[12:13], 1, v151
	v_cndmask_b32_e64 v148, 0, v229, s[8:9]
	v_cndmask_b32_e64 v149, 0, v229, s[10:11]
	v_cndmask_b32_e64 v76, 0, v229, s[12:13]
	v_perm_b32 v148, v148, v176, s3
	v_perm_b32 v149, v76, v149, s3
	v_mov_b32_e32 v151, v150
	s_waitcnt vmcnt(7)
	v_and_b32_e32 v173, 0xffff0000, v164
	v_lshlrev_b32_e32 v172, 16, v164
	v_mfma_f32_16x16x32_bf16 v[76:79], v[84:87], v[148:151], v[168:171]
	v_mul_f32_e64 v172, v172, s24
	v_mul_f32_e64 v173, v173, s24
	s_nop 5
	v_mul_f32_e32 v153, 0x3fb8aa3b, v76
	v_exp_f32_e32 v154, v153
	v_mul_f32_e32 v153, 0x3fb8aa3b, v77
	v_mul_f32_e32 v76, 0xbfb8aa3b, v76
	v_exp_f32_e32 v155, v153
	v_mul_f32_e32 v77, 0xbfb8aa3b, v77
	v_exp_f32_e32 v76, v76
	v_exp_f32_e32 v77, v77
	v_pk_mul_f32 v[154:155], v[172:173], v[154:155]
	s_waitcnt vmcnt(5)
	v_and_b32_e32 v173, 0xffff0000, v160
	v_lshlrev_b32_e32 v172, 16, v160
	v_pk_mul_f32 v[178:179], v[76:77], v[172:173]
	v_mul_f32_e32 v77, 0xbfb8aa3b, v78
	v_mul_f32_e32 v76, 0x3fb8aa3b, v78
	v_exp_f32_e32 v78, v77
	v_mul_f32_e32 v77, 0x3fb8aa3b, v79
	v_exp_f32_e32 v76, v76
	v_exp_f32_e32 v77, v77
	v_and_b32_e32 v173, 0xffff0000, v165
	v_lshlrev_b32_e32 v172, 16, v165
	v_pk_mul_f32 v[164:165], v[172:173], s[24:25] op_sel_hi:[1,0]
	v_mfma_f32_16x16x32_bf16 v[172:175], v[96:99], v[246:249], 0
	v_mul_f32_e64 v164, v164, v76
	v_mul_f32_e64 v165, v165, v77
	v_mul_f32_e32 v76, 0xbfb8aa3b, v79
	v_exp_f32_e32 v79, v76
	v_and_b32_e32 v77, 0xffff0000, v161
	v_lshlrev_b32_e32 v76, 16, v161
	v_and_b32_e32 v161, 0xffff0000, v166
	v_pk_mul_f32 v[98:99], v[78:79], v[76:77]
	v_mfma_f32_16x16x32_bf16 v[76:79], v[100:103], v[148:151], v[172:175]
	v_lshlrev_b32_e32 v160, 16, v166
	v_pk_mul_f32 v[160:161], v[160:161], s[24:25] op_sel_hi:[1,0]
	s_nop 5
	v_mul_f32_e32 v96, 0x3fb8aa3b, v76
	v_mul_f32_e32 v97, 0x3fb8aa3b, v77
	v_exp_f32_e32 v96, v96
	v_mul_f32_e32 v76, 0xbfb8aa3b, v76
	v_exp_f32_e32 v97, v97
	v_mul_f32_e32 v77, 0xbfb8aa3b, v77
	v_exp_f32_e32 v76, v76
	v_exp_f32_e32 v77, v77
	v_pk_mul_f32 v[96:97], v[160:161], v[96:97]
	v_and_b32_e32 v161, 0xffff0000, v162
	v_lshlrev_b32_e32 v160, 16, v162
	v_pk_mul_f32 v[180:181], v[76:77], v[160:161]
	v_mul_f32_e32 v77, 0xbfb8aa3b, v78
	v_mul_f32_e32 v76, 0x3fb8aa3b, v78
	v_exp_f32_e32 v78, v77
	v_mul_f32_e32 v77, 0x3fb8aa3b, v79
	v_exp_f32_e32 v76, v76
	v_exp_f32_e32 v77, v77
	v_mul_f32_e32 v79, 0xbfb8aa3b, v79
	v_exp_f32_e32 v79, v79
	v_and_b32_e32 v161, 0xffff0000, v167
	v_lshlrev_b32_e32 v160, 16, v167
	v_pk_mul_f32 v[160:161], v[160:161], s[24:25] op_sel_hi:[1,0]
	s_nop 0
	v_pk_mul_f32 v[160:161], v[160:161], v[76:77]
	v_and_b32_e32 v77, 0xffff0000, v163
	v_lshlrev_b32_e32 v76, 16, v163
	v_pk_mul_f32 v[166:167], v[78:79], v[76:77]
	v_cvt_pk_bf16_f32 v79, v160, v161
	v_mfma_f32_16x16x32_bf16 v[160:163], v[104:107], v[246:249], 0
	v_cvt_pk_bf16_f32 v76, v154, v155
	v_cvt_pk_bf16_f32 v77, v164, v165
	v_and_b32_e32 v165, 0xffff0000, v144
	v_mfma_f32_16x16x32_bf16 v[104:107], v[92:95], v[148:151], v[160:163]
	v_lshlrev_b32_e32 v164, 16, v144
	v_pk_mul_f32 v[164:165], v[164:165], s[24:25] op_sel_hi:[1,0]
	v_cvt_pk_bf16_f32 v78, v96, v97
	v_cvt_pk_bf16_f32 v97, v98, v99
	v_cvt_pk_bf16_f32 v99, v166, v167
	s_nop 2
	v_mul_f32_e32 v153, 0x3fb8aa3b, v104
	v_exp_f32_e32 v154, v153
	v_mul_f32_e32 v153, 0x3fb8aa3b, v105
	v_mul_f32_e32 v104, 0xbfb8aa3b, v104
	v_exp_f32_e32 v155, v153
	v_mul_f32_e32 v105, 0xbfb8aa3b, v105
	v_exp_f32_e32 v104, v104
	v_exp_f32_e32 v105, v105
	v_pk_mul_f32 v[154:155], v[164:165], v[154:155]
	s_waitcnt vmcnt(4)
; __device__ __forceinline__ float bf2f(bf16_t b) { return __uint_as_float(((unsigned)b) << 16); }
; __device__ __forceinline__ f32x4 mfma16(bf16x8 a, bf16x8 b, f32x4 c) { return __builtin_amdgcn_mfma_f32_16x16x32_bf16(a, b, c, 0, 0, 0); }
; template <int MODE> __device__ void mixer_gla(const Params& p, int l, int n, LAS unsigned char* lds) {
;     ...
;             for (int tj = 0; tj < 4; ++tj) {
;                 const int t = 16 * tj + c;
;                 bf16x8 mk[2];
; #pragma unroll
;                 for (int ks = 0; ks < 2; ++ks)
; #pragma unroll
;                     for (int jj = 0; jj < 8; ++jj) { const int sidx = SLOT(ks, q, jj); const bool on = dir == 0 ? sidx <= t : sidx >= t; mk[ks][jj] = on ? (short)0x3F80 : (short)0; }
; #pragma unroll
;                 for (int ks2 = 0; ks2 < 2; ++ks2) { f32x4 qe2[2], ke2[2];
; #pragma unroll
;                     for (int e2 = 0; e2 < 2; ++e2) { const int ef = 2 * ks2 + e2;
;                         f32x4 b = mfma16(laop[ef][0], mk[0], zero4); b = mfma16(laop[ef][1], mk[1], b);
; #pragma unroll
;                         for (int r = 0; r < 4; ++r) { qe2[e2][r] = bf2f((bf16_t)qn[tj][ks2][4 * e2 + r]) * 0.125f * __expf(b[r]); ke2[e2][r] = bf2f((bf16_t)kn1[tj][ks2][4 * e2 + r]) * __expf(-b[r]); } }
;                     QEop[tj][ks2] = pack8(qe2[0], qe2[1]); KEop[tj][ks2] = pack8(ke2[0], ke2[1]); }
	v_and_b32_e32 v165, 0xffff0000, v140
	v_lshlrev_b32_e32 v164, 16, v140
	v_mul_f32_e32 v140, 0x3fb8aa3b, v106
	v_pk_mul_f32 v[104:105], v[104:105], v[164:165]
	v_exp_f32_e32 v164, v140
	v_mul_f32_e32 v140, 0x3fb8aa3b, v107
	v_exp_f32_e32 v165, v140
	v_and_b32_e32 v167, 0xffff0000, v145
	v_lshlrev_b32_e32 v166, 16, v145
	v_mul_f32_e32 v106, 0xbfb8aa3b, v106
	v_pk_mul_f32 v[144:145], v[166:167], s[24:25] op_sel_hi:[1,0]
	v_mul_f32_e32 v107, 0xbfb8aa3b, v107
	v_exp_f32_e32 v106, v106
	v_pk_mul_f32 v[144:145], v[144:145], v[164:165]
	v_exp_f32_e32 v107, v107
	v_mfma_f32_16x16x32_bf16 v[164:167], v[80:83], v[246:249], 0
	v_and_b32_e32 v81, 0xffff0000, v141
	v_lshlrev_b32_e32 v80, 16, v141
	v_pk_mul_f32 v[106:107], v[106:107], v[80:81]
	v_mfma_f32_16x16x32_bf16 v[80:83], v[112:115], v[148:151], v[164:167]
	v_and_b32_e32 v149, 0xffff0000, v146
	v_lshlrev_b32_e32 v148, 16, v146
	v_pk_mul_f32 v[148:149], v[148:149], s[24:25] op_sel_hi:[1,0]
	v_and_b32_e32 v151, 0xffff0000, v147
	v_lshlrev_b32_e32 v150, 16, v147
	s_nop 2
	v_mul_f32_e32 v140, 0x3fb8aa3b, v80
	v_mul_f32_e32 v141, 0x3fb8aa3b, v81
	v_exp_f32_e32 v140, v140
	v_mul_f32_e32 v80, 0xbfb8aa3b, v80
	v_exp_f32_e32 v141, v141
	v_mul_f32_e32 v81, 0xbfb8aa3b, v81
	v_exp_f32_e32 v80, v80
	v_exp_f32_e32 v81, v81
	v_pk_mul_f32 v[140:141], v[148:149], v[140:141]
	v_and_b32_e32 v149, 0xffff0000, v142
	v_lshlrev_b32_e32 v148, 16, v142
	v_pk_mul_f32 v[148:149], v[80:81], v[148:149]
	v_mul_f32_e32 v81, 0xbfb8aa3b, v82
	v_mul_f32_e32 v80, 0x3fb8aa3b, v82
	v_exp_f32_e32 v82, v81
	v_mul_f32_e32 v81, 0x3fb8aa3b, v83
	v_exp_f32_e32 v80, v80
	v_exp_f32_e32 v81, v81
	v_mul_f32_e32 v83, 0xbfb8aa3b, v83
	v_exp_f32_e32 v83, v83
	v_pk_mul_f32 v[146:147], v[150:151], s[24:25] op_sel_hi:[1,0]
	v_cvt_pk_bf16_f32 v96, v178, v179
	v_pk_mul_f32 v[146:147], v[146:147], v[80:81]
	v_and_b32_e32 v81, 0xffff0000, v143
	v_lshlrev_b32_e32 v80, 16, v143
	v_pk_mul_f32 v[142:143], v[82:83], v[80:81]
	v_cvt_pk_bf16_f32 v98, v180, v181
	v_cvt_pk_bf16_f32 v80, v154, v155
	v_cvt_pk_bf16_f32 v81, v144, v145
	v_cvt_pk_bf16_f32 v82, v140, v141
	v_cvt_pk_bf16_f32 v83, v146, v147
	v_cvt_pk_bf16_f32 v104, v104, v105
	v_cvt_pk_bf16_f32 v105, v106, v107
	v_cvt_pk_bf16_f32 v106, v148, v149
	v_cvt_pk_bf16_f32 v107, v142, v143
	v_cndmask_b32_e64 v140, 0, 1, s[80:81]
	v_cndmask_b32_e64 v141, 0, 1, s[82:83]
	v_cndmask_b32_e64 v140, v141, v140, s[26:27]
	v_and_b32_e32 v140, 1, v140
	v_cmp_eq_u32_e64 s[0:1], 1, v140
	v_cndmask_b32_e64 v141, 0, 1, s[86:87]
	v_cndmask_b32_e64 v142, 0, 1, s[90:91]
	v_cndmask_b32_e64 v140, 0, v229, s[0:1]
	v_perm_b32 v154, v140, v176, s3
	v_cndmask_b32_e64 v140, 0, 1, s[84:85]
	v_cndmask_b32_e64 v140, v141, v140, s[26:27]
	v_cndmask_b32_e64 v141, 0, 1, s[88:89]
	v_cndmask_b32_e64 v141, v142, v141, s[26:27]
	v_and_b32_e32 v140, 1, v140
	v_and_b32_e32 v141, 1, v141
	v_cmp_eq_u32_e64 s[18:19], 1, v140
	v_cmp_eq_u32_e64 s[22:23], 1, v141
	v_mov_b32_e32 v153, v152
	v_cndmask_b32_e64 v140, 0, v229, s[18:19]
	v_cndmask_b32_e64 v141, 0, v229, s[22:23]
	v_perm_b32 v155, v141, v140, s3
	s_waitcnt vmcnt(3)
	v_and_b32_e32 v143, 0xffff0000, v128
	v_lshlrev_b32_e32 v142, 16, v128
	v_mfma_f32_16x16x32_bf16 v[84:87], v[84:87], v[152:155], v[168:171]
	v_mul_f32_e64 v142, v142, s24
	v_mul_f32_e64 v143, v143, s24
	v_and_b32_e32 v145, 0xffff0000, v129
	v_lshlrev_b32_e32 v144, 16, v129
	v_pk_mul_f32 v[128:129], v[144:145], s[24:25] op_sel_hi:[1,0]
	v_mfma_f32_16x16x32_bf16 v[92:95], v[92:95], v[152:155], v[160:163]
	s_nop 1
	v_mul_f32_e32 v140, 0x3fb8aa3b, v84
	v_mul_f32_e32 v141, 0x3fb8aa3b, v85
	v_exp_f32_e32 v140, v140
	v_mul_f32_e32 v84, 0xbfb8aa3b, v84
	v_exp_f32_e32 v141, v141
	v_mul_f32_e32 v85, 0xbfb8aa3b, v85
	v_exp_f32_e32 v84, v84
	v_exp_f32_e32 v85, v85
	v_pk_mul_f32 v[140:141], v[142:143], v[140:141]
	s_waitcnt vmcnt(1)
	v_and_b32_e32 v143, 0xffff0000, v124
	v_lshlrev_b32_e32 v142, 16, v124
	v_pk_mul_f32 v[142:143], v[84:85], v[142:143]
	v_mul_f32_e32 v85, 0xbfb8aa3b, v86
	v_mul_f32_e32 v84, 0x3fb8aa3b, v86
	v_exp_f32_e32 v86, v85
	v_mul_f32_e32 v85, 0x3fb8aa3b, v87
	v_exp_f32_e32 v84, v84
	v_exp_f32_e32 v85, v85
	v_mul_f32_e32 v87, 0xbfb8aa3b, v87
	v_exp_f32_e32 v87, v87
	v_and_b32_e32 v145, 0xffff0000, v131
	v_pk_mul_f32 v[128:129], v[128:129], v[84:85]
	v_and_b32_e32 v85, 0xffff0000, v125
	v_lshlrev_b32_e32 v84, 16, v125
	v_pk_mul_f32 v[124:125], v[86:87], v[84:85]
	v_mfma_f32_16x16x32_bf16 v[84:87], v[100:103], v[152:155], v[172:175]
	v_and_b32_e32 v103, 0xffff0000, v130
	v_lshlrev_b32_e32 v102, 16, v130
	v_pk_mul_f32 v[102:103], v[102:103], s[24:25] op_sel_hi:[1,0]
	v_lshlrev_b32_e32 v144, 16, v131
	v_pk_mul_f32 v[130:131], v[144:145], s[24:25] op_sel_hi:[1,0]
	s_nop 2
	v_mul_f32_e32 v100, 0x3fb8aa3b, v84
	v_mul_f32_e32 v101, 0x3fb8aa3b, v85
	v_exp_f32_e32 v100, v100
	v_mul_f32_e32 v84, 0xbfb8aa3b, v84
	v_exp_f32_e32 v101, v101
	v_mul_f32_e32 v85, 0xbfb8aa3b, v85
	v_exp_f32_e32 v84, v84
	v_exp_f32_e32 v85, v85
	v_pk_mul_f32 v[100:101], v[102:103], v[100:101]
	v_and_b32_e32 v103, 0xffff0000, v126
	v_lshlrev_b32_e32 v102, 16, v126
	v_pk_mul_f32 v[102:103], v[84:85], v[102:103]
	v_mul_f32_e32 v85, 0xbfb8aa3b, v86
	v_mul_f32_e32 v84, 0x3fb8aa3b, v86
	v_exp_f32_e32 v86, v85
	v_mul_f32_e32 v85, 0x3fb8aa3b, v87
	v_exp_f32_e32 v84, v84
	v_exp_f32_e32 v85, v85
	v_mul_f32_e32 v87, 0xbfb8aa3b, v87
	v_exp_f32_e32 v87, v87
	v_cvt_pk_bf16_f32 v102, v102, v103
	v_pk_mul_f32 v[130:131], v[130:131], v[84:85]
	v_and_b32_e32 v85, 0xffff0000, v127
	v_lshlrev_b32_e32 v84, 16, v127
	v_pk_mul_f32 v[126:127], v[86:87], v[84:85]
	v_cvt_pk_bf16_f32 v86, v100, v101
	v_cvt_pk_bf16_f32 v101, v124, v125
	v_mul_f32_e32 v124, 0x3fb8aa3b, v92
	v_mul_f32_e32 v125, 0x3fb8aa3b, v93
	v_exp_f32_e32 v124, v124
	v_mul_f32_e32 v92, 0xbfb8aa3b, v92
	v_exp_f32_e32 v125, v125
	v_mul_f32_e32 v93, 0xbfb8aa3b, v93
	v_exp_f32_e32 v92, v92
	v_exp_f32_e32 v93, v93
	v_cvt_pk_bf16_f32 v103, v126, v127
	v_and_b32_e32 v127, 0xffff0000, v108
	v_lshlrev_b32_e32 v126, 16, v108
	v_pk_mul_f32 v[126:127], v[126:127], s[24:25] op_sel_hi:[1,0]
	v_cvt_pk_bf16_f32 v85, v128, v129
	v_pk_mul_f32 v[124:125], v[126:127], v[124:125]
	s_waitcnt vmcnt(0)
; __device__ __forceinline__ float bf2f(bf16_t b) { return __uint_as_float(((unsigned)b) << 16); }
; __device__ __forceinline__ f32x4 mfma16(bf16x8 a, bf16x8 b, f32x4 c) { return __builtin_amdgcn_mfma_f32_16x16x32_bf16(a, b, c, 0, 0, 0); }
; template <int MODE> __device__ void mixer_gla(const Params& p, int l, int n, LAS unsigned char* lds) {
;     ...
;                 for (int ks2 = 0; ks2 < 2; ++ks2) { f32x4 qe2[2], ke2[2];
; #pragma unroll
;                     for (int e2 = 0; e2 < 2; ++e2) { const int ef = 2 * ks2 + e2;
;                         f32x4 b = mfma16(laop[ef][0], mk[0], zero4); b = mfma16(laop[ef][1], mk[1], b);
; #pragma unroll
;                         for (int r = 0; r < 4; ++r) { qe2[e2][r] = bf2f((bf16_t)qn[tj][ks2][4 * e2 + r]) * 0.125f * __expf(b[r]); ke2[e2][r] = bf2f((bf16_t)kn1[tj][ks2][4 * e2 + r]) * __expf(-b[r]); } }
;                     QEop[tj][ks2] = pack8(qe2[0], qe2[1]); KEop[tj][ks2] = pack8(ke2[0], ke2[1]); }
;                 __builtin_amdgcn_sched_barrier(0);
;             }
;             const bf16_t* SP = spT + ((size_t)(dir * NCH + n) * 4 + h) * 8192 + (size_t)(64 * vh) * 64;
;             bf16x8 spf[4][2];
; #pragma unroll
;             for (int vf = 0; vf < 4; ++vf)
; #pragma unroll
;                 for (int ks = 0; ks < 2; ++ks) spf[vf][ks] = *(const bf16x8*)(SP + (16 * vf + c) * 64 + 32 * ks + 8 * q);
;             __builtin_amdgcn_sched_barrier(0);
;             bf16x8 Pop[4][2];
; #pragma unroll
;             for (int ti = 0; ti < 4; ++ti)
; #pragma unroll
;                 for (int ksp = 0; ksp < 2; ++ksp) { f32x4 pm[2];
; #pragma unroll
;                     for (int j2 = 0; j2 < 2; ++j2) { const int tjj = 2 * ksp + j2;
;                         f32x4 sc = mfma16(KEop[tjj][0], QEop[ti][0], zero4); sc = mfma16(KEop[tjj][1], QEop[ti][1], sc);
; #pragma unroll
;                         for (int r = 0; r < 4; ++r) { const int j = 16 * tjj + 4 * q + r, i = 16 * ti + c; const bool keep = dir == 0 ? j <= i : j >= i; pm[j2][r] = keep ? sc[r] : 0.f; } }
;                     Pop[ti][ksp] = pack8(pm[0], pm[1]); __builtin_amdgcn_sched_barrier(0); }
	v_and_b32_e32 v127, 0xffff0000, v88
	v_lshlrev_b32_e32 v126, 16, v88
	v_mul_f32_e32 v88, 0x3fb8aa3b, v94
	v_pk_mul_f32 v[126:127], v[92:93], v[126:127]
	v_exp_f32_e32 v92, v88
	v_mul_f32_e32 v88, 0xbfb8aa3b, v94
	v_exp_f32_e32 v94, v88
	v_mul_f32_e32 v88, 0x3fb8aa3b, v95
	v_exp_f32_e32 v93, v88
	v_mul_f32_e32 v88, 0xbfb8aa3b, v95
	v_exp_f32_e32 v95, v88
	v_and_b32_e32 v129, 0xffff0000, v109
	v_lshlrev_b32_e32 v128, 16, v109
	v_pk_mul_f32 v[108:109], v[128:129], s[24:25] op_sel_hi:[1,0]
	v_cvt_pk_bf16_f32 v84, v140, v141
	v_pk_mul_f32 v[108:109], v[108:109], v[92:93]
	v_and_b32_e32 v93, 0xffff0000, v89
	v_lshlrev_b32_e32 v92, 16, v89
	v_pk_mul_f32 v[128:129], v[94:95], v[92:93]
	v_mfma_f32_16x16x32_bf16 v[92:95], v[112:115], v[152:155], v[164:167]
	v_and_b32_e32 v113, 0xffff0000, v110
	v_lshlrev_b32_e32 v112, 16, v110
	v_pk_mul_f32 v[112:113], v[112:113], s[24:25] op_sel_hi:[1,0]
	v_and_b32_e32 v115, 0xffff0000, v111
	v_lshlrev_b32_e32 v114, 16, v111
	s_nop 2
	v_mul_f32_e32 v89, 0xbfb8aa3b, v92
	v_mul_f32_e32 v88, 0x3fb8aa3b, v92
	v_exp_f32_e32 v92, v89
	v_mul_f32_e32 v89, 0x3fb8aa3b, v93
	v_exp_f32_e32 v88, v88
	v_exp_f32_e32 v89, v89
	v_mul_f32_e32 v93, 0xbfb8aa3b, v93
	v_exp_f32_e32 v93, v93
	v_pk_mul_f32 v[110:111], v[114:115], s[24:25] op_sel_hi:[1,0]
	v_pk_mul_f32 v[112:113], v[112:113], v[88:89]
	v_and_b32_e32 v89, 0xffff0000, v90
	v_lshlrev_b32_e32 v88, 16, v90
	v_pk_mul_f32 v[92:93], v[92:93], v[88:89]
	v_mul_f32_e32 v89, 0xbfb8aa3b, v94
	v_mul_f32_e32 v88, 0x3fb8aa3b, v94
	v_exp_f32_e32 v94, v89
	v_mul_f32_e32 v89, 0x3fb8aa3b, v95
	v_exp_f32_e32 v88, v88
	v_exp_f32_e32 v89, v89
	v_mul_f32_e32 v90, 0xbfb8aa3b, v95
	v_exp_f32_e32 v95, v90
	v_cvt_pk_bf16_f32 v87, v130, v131
	v_pk_mul_f32 v[110:111], v[110:111], v[88:89]
	v_and_b32_e32 v89, 0xffff0000, v91
	v_lshlrev_b32_e32 v88, 16, v91
	v_pk_mul_f32 v[94:95], v[94:95], v[88:89]
	v_cvt_pk_bf16_f32 v100, v142, v143
	v_cvt_pk_bf16_f32 v88, v124, v125
	v_cvt_pk_bf16_f32 v89, v108, v109
	v_cvt_pk_bf16_f32 v90, v112, v113
	v_cvt_pk_bf16_f32 v91, v110, v111
	v_cvt_pk_bf16_f32 v148, v126, v127
	v_cvt_pk_bf16_f32 v149, v128, v129
	v_cvt_pk_bf16_f32 v150, v92, v93
	v_cvt_pk_bf16_f32 v151, v94, v95
	s_add_i32 s14, s34, s43
	s_ashr_i32 s15, s14, 31
	s_lshl_b64 s[14:15], s[14:15], 16
	v_lshl_add_u64 v[92:93], v[220:221], 0, s[14:15]
	s_movk_i32 s2, 0x1000
	global_load_dwordx4 v[152:155], v[92:93], off
	global_load_dwordx4 v[160:163], v[92:93], off offset:64
	global_load_dwordx4 v[164:167], v[92:93], off offset:2048
	global_load_dwordx4 v[144:147], v[92:93], off offset:2112
	v_add_co_u32_e32 v92, vcc, s2, v92
	s_nop 1
	v_addc_co_u32_e32 v93, vcc, 0, v93, vcc
	global_load_dwordx4 v[128:131], v[92:93], off
	global_load_dwordx4 v[112:115], v[92:93], off offset:64
	global_load_dwordx4 v[108:111], v[92:93], off offset:2048
	s_nop 0
	global_load_dwordx4 v[92:95], v[92:93], off offset:2112
	v_mfma_f32_16x16x32_bf16 v[124:127], v[72:75], v[64:67], 0
	v_mfma_f32_16x16x32_bf16 v[124:127], v[120:123], v[68:71], v[124:127]
	v_mfma_f32_16x16x32_bf16 v[140:143], v[136:139], v[64:67], 0
	s_nop 6
	v_cndmask_b32_e64 v168, 0, v124, s[16:17]
	v_cndmask_b32_e64 v169, 0, v125, s[92:93]
	v_cndmask_b32_e64 v170, 0, v126, s[94:95]
	v_cndmask_b32_e64 v171, 0, v127, s[96:97]
	v_mfma_f32_16x16x32_bf16 v[124:127], v[156:159], v[68:71], v[140:143]
	s_nop 7
	v_cndmask_b32_e64 v140, v124, 0, s[26:27]
	v_cndmask_b32_e64 v141, v125, 0, s[26:27]
	v_cndmask_b32_e64 v142, v126, 0, s[26:27]
	v_cndmask_b32_e64 v127, v127, 0, s[26:27]
	v_cvt_pk_bf16_f32 v124, v168, v169
	v_cvt_pk_bf16_f32 v125, v170, v171
	v_cvt_pk_bf16_f32 v126, v140, v141
	v_cvt_pk_bf16_f32 v127, v142, v127
	v_mfma_f32_16x16x32_bf16 v[140:143], v[96:99], v[64:67], 0
	v_mfma_f32_16x16x32_bf16 v[140:143], v[104:107], v[68:71], v[140:143]
	v_mfma_f32_16x16x32_bf16 v[168:171], v[100:103], v[64:67], 0
	s_nop 6
	v_cndmask_b32_e64 v172, v140, 0, s[26:27]
	v_cndmask_b32_e64 v173, v141, 0, s[26:27]
	v_cndmask_b32_e64 v174, v142, 0, s[26:27]
	v_cndmask_b32_e64 v175, v143, 0, s[26:27]
	v_mfma_f32_16x16x32_bf16 v[140:143], v[148:151], v[68:71], v[168:171]
	s_nop 7
	v_cndmask_b32_e64 v168, v140, 0, s[26:27]
	v_cndmask_b32_e64 v169, v141, 0, s[26:27]
	v_cndmask_b32_e64 v170, v142, 0, s[26:27]
	v_cndmask_b32_e64 v143, v143, 0, s[26:27]
	v_cvt_pk_bf16_f32 v140, v172, v173
	v_cvt_pk_bf16_f32 v141, v174, v175
	v_cvt_pk_bf16_f32 v142, v168, v169
	v_cvt_pk_bf16_f32 v143, v170, v143
	v_mfma_f32_16x16x32_bf16 v[168:171], v[72:75], v[116:119], 0
	v_mfma_f32_16x16x32_bf16 v[168:171], v[120:123], v[132:135], v[168:171]
	v_mfma_f32_16x16x32_bf16 v[172:175], v[136:139], v[116:119], 0
	s_nop 6
	v_cndmask_b32_e64 v176, 0, v168, s[26:27]
	v_cndmask_b32_e64 v178, 0, v169, s[26:27]
	v_cndmask_b32_e64 v179, 0, v170, s[26:27]
	v_cndmask_b32_e64 v180, 0, v171, s[26:27]
	v_mfma_f32_16x16x32_bf16 v[168:171], v[156:159], v[132:135], v[172:175]
	s_nop 7
	v_cndmask_b32_e64 v172, 0, v168, s[16:17]
	v_cndmask_b32_e64 v173, 0, v169, s[20:21]
	v_cndmask_b32_e64 v174, 0, v170, s[4:5]
	v_cndmask_b32_e64 v171, 0, v171, s[6:7]
	v_cvt_pk_bf16_f32 v168, v176, v178
	v_cvt_pk_bf16_f32 v169, v179, v180
	v_cvt_pk_bf16_f32 v170, v172, v173
	v_cvt_pk_bf16_f32 v171, v174, v171
	v_mfma_f32_16x16x32_bf16 v[172:175], v[96:99], v[116:119], 0
	v_mfma_f32_16x16x32_bf16 v[172:175], v[104:107], v[132:135], v[172:175]
	v_mfma_f32_16x16x32_bf16 v[246:249], v[100:103], v[116:119], 0
	s_nop 6
	v_cndmask_b32_e64 v176, v172, 0, s[26:27]
	v_cndmask_b32_e64 v178, v173, 0, s[26:27]
	v_cndmask_b32_e64 v179, v174, 0, s[26:27]
	v_cndmask_b32_e64 v180, v175, 0, s[26:27]
	v_mfma_f32_16x16x32_bf16 v[172:175], v[148:151], v[132:135], v[246:249]
; #define LAS __attribute__((address_space(3)))
; __device__ __forceinline__ f32x4 mfma16(bf16x8 a, bf16x8 b, f32x4 c) { return __builtin_amdgcn_mfma_f32_16x16x32_bf16(a, b, c, 0, 0, 0); }
; template <int MODE> __device__ void mixer_gla(const Params& p, int l, int n, LAS unsigned char* lds) {
;     ...
;             for (int ti = 0; ti < 4; ++ti)
; #pragma unroll
;                 for (int ksp = 0; ksp < 2; ++ksp) { f32x4 pm[2];
; #pragma unroll
;                     for (int j2 = 0; j2 < 2; ++j2) { const int tjj = 2 * ksp + j2;
;                         f32x4 sc = mfma16(KEop[tjj][0], QEop[ti][0], zero4); sc = mfma16(KEop[tjj][1], QEop[ti][1], sc);
; #pragma unroll
;                         for (int r = 0; r < 4; ++r) { const int j = 16 * tjj + 4 * q + r, i = 16 * ti + c; const bool keep = dir == 0 ? j <= i : j >= i; pm[j2][r] = keep ? sc[r] : 0.f; } }
;                     Pop[ti][ksp] = pack8(pm[0], pm[1]); __builtin_amdgcn_sched_barrier(0); }
; #pragma unroll
;             for (int vf = 0; vf < 4; ++vf)
; #pragma unroll
;                 for (int ks = 0; ks < 2; ++ks) {
;                     const u32x2 v0 = *(const LAS u32x2*)(VTw + (16 * vf + c) * 72 + 32 * ks + 4 * q), v1 = *(const LAS u32x2*)(VTw + (16 * vf + c) * 72 + 32 * ks + 16 + 4 * q);
;                     const bf16x8 vtf = __builtin_bit_cast(bf16x8, (u32x4){v0.x, v0.y, v1.x, v1.y});
; #pragma unroll
;                     for (int ti = 0; ti < 4; ++ti) { acc[vf][ti] = mfma16(vtf, Pop[ti][ks], acc[vf][ti]); acc[vf][ti] = mfma16(spf[vf][ks], QEop[ti][ks], acc[vf][ti]); }
	s_nop 7
	v_cndmask_b32_e64 v181, v172, 0, s[26:27]
	v_cndmask_b32_e64 v188, v173, 0, s[26:27]
	v_cndmask_b32_e64 v189, v174, 0, s[26:27]
	v_cndmask_b32_e64 v175, v175, 0, s[26:27]
	v_cvt_pk_bf16_f32 v172, v176, v178
	v_cvt_pk_bf16_f32 v173, v179, v180
	v_cvt_pk_bf16_f32 v174, v181, v188
	v_cvt_pk_bf16_f32 v175, v189, v175
	v_mfma_f32_16x16x32_bf16 v[246:249], v[72:75], v[76:79], 0
	v_mfma_f32_16x16x32_bf16 v[178:181], v[136:139], v[76:79], 0
	v_mfma_f32_16x16x32_bf16 v[246:249], v[120:123], v[80:83], v[246:249]
	v_mfma_f32_16x16x32_bf16 v[178:181], v[156:159], v[80:83], v[178:181]
	s_nop 6
	v_cndmask_b32_e64 v176, 0, v246, s[26:27]
	v_cndmask_b32_e64 v188, 0, v247, s[26:27]
	v_cndmask_b32_e64 v189, 0, v248, s[26:27]
	v_cndmask_b32_e64 v190, 0, v249, s[26:27]
	v_cndmask_b32_e64 v191, 0, v178, s[26:27]
	v_cndmask_b32_e64 v201, 0, v179, s[26:27]
	v_cndmask_b32_e64 v246, 0, v180, s[26:27]
	v_cndmask_b32_e64 v181, 0, v181, s[26:27]
	v_cvt_pk_bf16_f32 v178, v176, v188
	v_cvt_pk_bf16_f32 v179, v189, v190
	v_cvt_pk_bf16_f32 v180, v191, v201
	v_cvt_pk_bf16_f32 v181, v246, v181
	v_mfma_f32_16x16x32_bf16 v[246:249], v[96:99], v[76:79], 0
	v_mfma_f32_16x16x32_bf16 v[188:191], v[100:103], v[76:79], 0
	v_mfma_f32_16x16x32_bf16 v[246:249], v[104:107], v[80:83], v[246:249]
	v_mfma_f32_16x16x32_bf16 v[188:191], v[148:151], v[80:83], v[188:191]
	s_nop 6
	v_cndmask_b32_e64 v176, 0, v246, s[16:17]
	v_cndmask_b32_e64 v201, 0, v247, s[8:9]
	v_cndmask_b32_e64 v246, 0, v248, s[10:11]
	v_cndmask_b32_e64 v247, 0, v249, s[12:13]
	v_cndmask_b32_e64 v248, v188, 0, s[26:27]
	v_cndmask_b32_e64 v249, v189, 0, s[26:27]
	v_cndmask_b32_e64 v224, v190, 0, s[26:27]
	v_cndmask_b32_e64 v191, v191, 0, s[26:27]
	v_cvt_pk_bf16_f32 v188, v176, v201
	v_cvt_pk_bf16_f32 v189, v246, v247
	v_cvt_pk_bf16_f32 v190, v248, v249
	v_cvt_pk_bf16_f32 v191, v224, v191
	v_mfma_f32_16x16x32_bf16 v[72:75], v[72:75], v[84:87], 0
	v_mfma_f32_16x16x32_bf16 v[72:75], v[120:123], v[88:91], v[72:75]
	v_mfma_f32_16x16x32_bf16 v[120:123], v[136:139], v[84:87], 0
	s_nop 6
	v_cndmask_b32_e64 v176, 0, v72, s[26:27]
	v_cndmask_b32_e64 v136, 0, v73, s[26:27]
	v_cndmask_b32_e64 v137, 0, v74, s[26:27]
	v_cndmask_b32_e64 v138, 0, v75, s[26:27]
	v_mfma_f32_16x16x32_bf16 v[72:75], v[156:159], v[88:91], v[120:123]
	s_nop 7
	v_cndmask_b32_e64 v120, 0, v72, s[26:27]
	v_cndmask_b32_e64 v121, 0, v73, s[26:27]
	v_cndmask_b32_e64 v122, 0, v74, s[26:27]
	v_cndmask_b32_e64 v75, 0, v75, s[26:27]
	v_cvt_pk_bf16_f32 v72, v176, v136
	v_cvt_pk_bf16_f32 v73, v137, v138
	v_cvt_pk_bf16_f32 v74, v120, v121
	v_cvt_pk_bf16_f32 v75, v122, v75
	v_mfma_f32_16x16x32_bf16 v[96:99], v[96:99], v[84:87], 0
	v_mfma_f32_16x16x32_bf16 v[96:99], v[104:107], v[88:91], v[96:99]
	v_mfma_f32_16x16x32_bf16 v[100:103], v[100:103], v[84:87], 0
	s_nop 6
	v_cndmask_b32_e64 v104, 0, v96, s[26:27]
	v_cndmask_b32_e64 v105, 0, v97, s[26:27]
	v_cndmask_b32_e64 v106, 0, v98, s[26:27]
	v_cndmask_b32_e64 v107, 0, v99, s[26:27]
	v_mfma_f32_16x16x32_bf16 v[96:99], v[148:151], v[88:91], v[100:103]
	s_nop 7
	v_cndmask_b32_e64 v100, 0, v96, s[16:17]
	v_cndmask_b32_e64 v101, 0, v97, s[0:1]
	v_cndmask_b32_e64 v102, 0, v98, s[18:19]
	v_cndmask_b32_e64 v99, 0, v99, s[22:23]
	v_cvt_pk_bf16_f32 v96, v104, v105
	v_cvt_pk_bf16_f32 v97, v106, v107
	v_cvt_pk_bf16_f32 v98, v100, v101
	v_cvt_pk_bf16_f32 v99, v102, v99
	ds_read2_b64 v[100:103], v199 offset1:4
	s_waitcnt lgkmcnt(0)
	v_mfma_f32_16x16x32_bf16 v[60:63], v[100:103], v[124:127], v[60:63]
	v_mfma_f32_16x16x32_bf16 v[44:47], v[100:103], v[168:171], v[44:47]
	v_mfma_f32_16x16x32_bf16 v[28:31], v[100:103], v[178:181], v[28:31]
	v_mfma_f32_16x16x32_bf16 v[12:15], v[100:103], v[72:75], v[12:15]
	ds_read2_b64 v[100:103], v199 offset0:8 offset1:12
	s_waitcnt vmcnt(7)
	v_mfma_f32_16x16x32_bf16 v[60:63], v[152:155], v[64:67], v[60:63]
	v_mfma_f32_16x16x32_bf16 v[44:47], v[152:155], v[116:119], v[44:47]
	v_mfma_f32_16x16x32_bf16 v[28:31], v[152:155], v[76:79], v[28:31]
	v_mfma_f32_16x16x32_bf16 v[12:15], v[152:155], v[84:87], v[12:15]
	s_waitcnt lgkmcnt(0)
	v_mfma_f32_16x16x32_bf16 v[60:63], v[100:103], v[140:143], v[60:63]
	v_mfma_f32_16x16x32_bf16 v[44:47], v[100:103], v[172:175], v[44:47]
	v_mfma_f32_16x16x32_bf16 v[28:31], v[100:103], v[188:191], v[28:31]
	v_mfma_f32_16x16x32_bf16 v[12:15], v[100:103], v[96:99], v[12:15]
	ds_read2_b64 v[100:103], v242 offset1:4
	s_waitcnt lgkmcnt(0)
	v_mfma_f32_16x16x32_bf16 v[56:59], v[100:103], v[124:127], v[56:59]
	v_mfma_f32_16x16x32_bf16 v[40:43], v[100:103], v[168:171], v[40:43]
	v_mfma_f32_16x16x32_bf16 v[24:27], v[100:103], v[178:181], v[24:27]
	v_mfma_f32_16x16x32_bf16 v[8:11], v[100:103], v[72:75], v[8:11]
	ds_read2_b64 v[100:103], v242 offset0:8 offset1:12
	s_waitcnt vmcnt(5)
; #define LAS __attribute__((address_space(3)))
; __device__ __forceinline__ f32x4 mfma16(bf16x8 a, bf16x8 b, f32x4 c) { return __builtin_amdgcn_mfma_f32_16x16x32_bf16(a, b, c, 0, 0, 0); }
; template <int MODE> __device__ void mixer_gla(const Params& p, int l, int n, LAS unsigned char* lds) {
;     ...
; #pragma unroll
;             for (int tt = 0; tt < 4; ++tt) { lrf[tt] = (bf16x8){0, 0, 0, 0, 0, 0, 0, 0}; if (q < 2) lrf[tt] = *(const bf16x8*)(proj + (size_t)(t0 + 16 * tt + c) * DINP + 2560 + dir * 16 + 8 * q); }
;     ...
; #pragma unroll
;             for (int vf = 0; vf < 4; ++vf)
; #pragma unroll
;                 for (int ks = 0; ks < 2; ++ks) {
;                     const u32x2 v0 = *(const LAS u32x2*)(VTw + (16 * vf + c) * 72 + 32 * ks + 4 * q), v1 = *(const LAS u32x2*)(VTw + (16 * vf + c) * 72 + 32 * ks + 16 + 4 * q);
;                     const bf16x8 vtf = __builtin_bit_cast(bf16x8, (u32x4){v0.x, v0.y, v1.x, v1.y});
; #pragma unroll
;                     for (int ti = 0; ti < 4; ++ti) { acc[vf][ti] = mfma16(vtf, Pop[ti][ks], acc[vf][ti]); acc[vf][ti] = mfma16(spf[vf][ks], QEop[ti][ks], acc[vf][ti]); }
;                     if (ks == 1 && (vf & 1)) __builtin_amdgcn_sched_barrier(0);
;                 }
	v_mfma_f32_16x16x32_bf16 v[56:59], v[164:167], v[64:67], v[56:59]
	v_mfma_f32_16x16x32_bf16 v[40:43], v[164:167], v[116:119], v[40:43]
	v_mfma_f32_16x16x32_bf16 v[24:27], v[164:167], v[76:79], v[24:27]
	v_mfma_f32_16x16x32_bf16 v[8:11], v[164:167], v[84:87], v[8:11]
	s_waitcnt lgkmcnt(0)
	v_mfma_f32_16x16x32_bf16 v[56:59], v[100:103], v[140:143], v[56:59]
	v_mfma_f32_16x16x32_bf16 v[40:43], v[100:103], v[172:175], v[40:43]
	v_mfma_f32_16x16x32_bf16 v[24:27], v[100:103], v[188:191], v[24:27]
	v_mfma_f32_16x16x32_bf16 v[8:11], v[100:103], v[96:99], v[8:11]
	v_mfma_f32_16x16x32_bf16 v[60:63], v[160:163], v[68:71], v[60:63]
	v_mfma_f32_16x16x32_bf16 v[44:47], v[160:163], v[132:135], v[44:47]
	v_mfma_f32_16x16x32_bf16 v[28:31], v[160:163], v[80:83], v[28:31]
	v_mfma_f32_16x16x32_bf16 v[12:15], v[160:163], v[88:91], v[12:15]
	s_waitcnt vmcnt(4)
	v_mfma_f32_16x16x32_bf16 v[56:59], v[144:147], v[68:71], v[56:59]
	v_mfma_f32_16x16x32_bf16 v[40:43], v[144:147], v[132:135], v[40:43]
	v_mfma_f32_16x16x32_bf16 v[24:27], v[144:147], v[80:83], v[24:27]
	v_mfma_f32_16x16x32_bf16 v[8:11], v[144:147], v[88:91], v[8:11]
	ds_read2_b64 v[100:103], v243 offset1:4
	s_waitcnt lgkmcnt(0)
	v_mfma_f32_16x16x32_bf16 v[52:55], v[100:103], v[124:127], v[52:55]
	v_mfma_f32_16x16x32_bf16 v[36:39], v[100:103], v[168:171], v[36:39]
	v_mfma_f32_16x16x32_bf16 v[20:23], v[100:103], v[178:181], v[20:23]
	v_mfma_f32_16x16x32_bf16 v[4:7], v[100:103], v[72:75], v[4:7]
	ds_read2_b64 v[100:103], v243 offset0:8 offset1:12
	s_waitcnt vmcnt(3)
	v_mfma_f32_16x16x32_bf16 v[52:55], v[128:131], v[64:67], v[52:55]
	v_mfma_f32_16x16x32_bf16 v[36:39], v[128:131], v[116:119], v[36:39]
	v_mfma_f32_16x16x32_bf16 v[20:23], v[128:131], v[76:79], v[20:23]
	v_mfma_f32_16x16x32_bf16 v[4:7], v[128:131], v[84:87], v[4:7]
	s_waitcnt lgkmcnt(0)
	v_mfma_f32_16x16x32_bf16 v[52:55], v[100:103], v[140:143], v[52:55]
	v_mfma_f32_16x16x32_bf16 v[36:39], v[100:103], v[172:175], v[36:39]
	v_mfma_f32_16x16x32_bf16 v[20:23], v[100:103], v[188:191], v[20:23]
	v_mfma_f32_16x16x32_bf16 v[4:7], v[100:103], v[96:99], v[4:7]
	ds_read2_b64 v[100:103], v244 offset1:4
	s_waitcnt lgkmcnt(0)
	v_mfma_f32_16x16x32_bf16 v[48:51], v[100:103], v[124:127], v[48:51]
	s_waitcnt vmcnt(1)
	v_mfma_f32_16x16x32_bf16 v[48:51], v[108:111], v[64:67], v[48:51]
	ds_read2_b64 v[64:67], v244 offset0:8 offset1:12
	v_mfma_f32_16x16x32_bf16 v[32:35], v[100:103], v[168:171], v[32:35]
	v_mfma_f32_16x16x32_bf16 v[16:19], v[100:103], v[178:181], v[16:19]
	v_mfma_f32_16x16x32_bf16 v[0:3], v[100:103], v[72:75], v[0:3]
	v_mfma_f32_16x16x32_bf16 v[32:35], v[108:111], v[116:119], v[32:35]
	v_mfma_f32_16x16x32_bf16 v[16:19], v[108:111], v[76:79], v[16:19]
	v_mfma_f32_16x16x32_bf16 v[0:3], v[108:111], v[84:87], v[0:3]
	s_waitcnt lgkmcnt(0)
	v_mfma_f32_16x16x32_bf16 v[48:51], v[64:67], v[140:143], v[48:51]
	v_mfma_f32_16x16x32_bf16 v[32:35], v[64:67], v[172:175], v[32:35]
	v_mfma_f32_16x16x32_bf16 v[16:19], v[64:67], v[188:191], v[16:19]
	v_mfma_f32_16x16x32_bf16 v[0:3], v[64:67], v[96:99], v[0:3]
	v_mfma_f32_16x16x32_bf16 v[52:55], v[112:115], v[68:71], v[52:55]
	v_mfma_f32_16x16x32_bf16 v[36:39], v[112:115], v[132:135], v[36:39]
	v_mfma_f32_16x16x32_bf16 v[20:23], v[112:115], v[80:83], v[20:23]
	v_mfma_f32_16x16x32_bf16 v[4:7], v[112:115], v[88:91], v[4:7]
	s_waitcnt vmcnt(0)
	v_mfma_f32_16x16x32_bf16 v[48:51], v[92:95], v[68:71], v[48:51]
	v_mfma_f32_16x16x32_bf16 v[32:35], v[92:95], v[132:135], v[32:35]
	v_mfma_f32_16x16x32_bf16 v[16:19], v[92:95], v[80:83], v[16:19]
	v_mfma_f32_16x16x32_bf16 v[0:3], v[92:95], v[88:91], v[0:3]
	s_mov_b32 s4, 1
	s_mov_b64 s[26:27], 0
	s_and_b64 vcc, exec, s[30:31]
	s_cbranch_vccnz .LBB0_160
.LBB0_152:
	s_lshl_b32 s5, s4, 4
	v_mov_b32_e32 v88, 0
	v_mov_b32_e32 v89, 0
	v_mov_b32_e32 v90, 0
	v_mov_b32_e32 v91, 0
	s_and_saveexec_b64 s[0:1], s[38:39]
	s_cbranch_execz .LBB0_154
	s_lshl_b32 s34, s5, 1
	v_lshl_add_u64 v[64:65], v[204:205], 0, s[34:35]
	s_nop 0
.LBB0_154:
	s_or_b64 exec, exec, s[0:1]
	v_mov_b32_e32 v72, 0
	v_mov_b32_e32 v80, 0
	v_mov_b32_e32 v81, 0
	v_mov_b32_e32 v82, 0
	v_mov_b32_e32 v83, 0
	s_and_saveexec_b64 s[0:1], s[38:39]
	s_cbranch_execz .LBB0_156
	s_lshl_b32 s34, s5, 1
	v_lshl_add_u64 v[64:65], v[206:207], 0, s[34:35]
	s_nop 0
.LBB0_156:
	s_or_b64 exec, exec, s[0:1]
	v_mov_b32_e32 v73, 0
	v_mov_b32_e32 v74, 0
	v_mov_b32_e32 v75, 0
	s_and_saveexec_b64 s[0:1], s[38:39]
	s_cbranch_execz .LBB0_158
	s_lshl_b32 s34, s5, 1
	v_lshl_add_u64 v[64:65], v[208:209], 0, s[34:35]
	s_nop 0
.LBB0_158:
	s_or_b64 exec, exec, s[0:1]
	v_mov_b32_e32 v64, 0
	v_mov_b32_e32 v65, 0
	v_mov_b32_e32 v66, 0
	v_mov_b32_e32 v67, 0
	s_and_saveexec_b64 s[0:1], s[38:39]
	s_cbranch_execz .LBB0_151
	s_lshl_b32 s34, s5, 1
	v_lshl_add_u64 v[64:65], v[210:211], 0, s[34:35]
	s_nop 0
	s_branch .LBB0_151

; __device__ __forceinline__ f32x4 mfma16(bf16x8 a, bf16x8 b, f32x4 c) { return __builtin_amdgcn_mfma_f32_16x16x32_bf16(a, b, c, 0, 0, 0); }
; template <int MODE> __device__ void mixer_gla(const Params& p, int l, int n, LAS unsigned char* lds) {
;     ...
;             bf16x8 kn[4][2];
; #pragma unroll
;             for (int tj = 0; tj < 4; ++tj)
; #pragma unroll
;                 for (int ks = 0; ks < 2; ++ks) kn[tj][ks] = *(const bf16x8*)(proj + (size_t)(t0 + 16 * tj + c) * DINP + 1280 + 64 * h + 32 * ks + 8 * q);
;             bf16x8 ident[2];
; #pragma unroll
;             for (int e1 = 0; e1 < 2; ++e1)
; #pragma unroll
;                 for (int jj = 0; jj < 8; ++jj) ident[e1][jj] = (8 * q + jj == 8 * (c >> 2) + 4 * e1 + (c & 3)) ? (short)0x3F80 : (short)0;
;             bf16x8 kdop[4][2];
; #pragma unroll
;             for (int ks = 0; ks < 2; ++ks) {
;                 bf16x8 mk[2][2];
; #pragma unroll
;                 for (int t2 = 0; t2 < 2; ++t2)
; #pragma unroll
;                     for (int k2 = 0; k2 < 2; ++k2)
; #pragma unroll
;                         for (int jj = 0; jj < 8; ++jj) { const int tp = 16 * (2 * ks + t2) + c, sidx = SLOT(k2, q, jj); const bool on = dir == 0 ? sidx > tp : sidx < tp; mk[t2][k2][jj] = on ? (short)0x3F80 : (short)0; }
; #pragma unroll
;                 for (int ef = 0; ef < 4; ++ef) { f32x4 kd2[2];
; #pragma unroll
;                     for (int t2 = 0; t2 < 2; ++t2) { const int tj = 2 * ks + t2;
;                         f32x4 E = mfma16(mk[t2][0], laop[ef][0], zero4); E = mfma16(mk[t2][1], laop[ef][1], E);
;                         const f32x4 kR = mfma16(kn[tj][ef >> 1], ident[ef & 1], zero4);
; #pragma unroll
;                         for (int r = 0; r < 4; ++r) kd2[t2][r] = kR[r] * __expf(E[r]); }
;                     kdop[ef][ks] = pack8(kd2[0], kd2[1]); __builtin_amdgcn_sched_barrier(0); }
.LBB0_329:
	s_or_b64 exec, exec, s[0:1]
	v_lshrrev_b32_e32 v134, 7, v245
	v_and_b32_e32 v135, 63, v245
	v_lshlrev_b32_e32 v134, 14, v134
	v_lshl_add_u32 v134, v135, 4, v134
	v_lshl_add_u32 v134, s5, 13, v134
	global_load_dwordx4 v[124:127], v[104:105], off offset:2560
	v_cvt_pk_bf16_f32 v76, v68, v69
	v_cvt_pk_bf16_f32 v78, v72, v73
	v_cvt_pk_bf16_f32 v79, v74, v75
	v_cvt_pk_bf16_f32 v68, v80, v81
	v_cvt_pk_bf16_f32 v69, v82, v83
	v_cvt_pk_bf16_f32 v60, v34, v35
	v_cvt_pk_bf16_f32 v61, v36, v37
	v_cvt_pk_bf16_f32 v63, v44, v45
	v_cvt_pk_bf16_f32 v52, v46, v47
	v_cvt_pk_bf16_f32 v55, v64, v65
	v_cvt_pk_bf16_f32 v44, v28, v29
	v_cvt_pk_bf16_f32 v46, v24, v25
	v_cvt_pk_bf16_f32 v47, v26, v27
	v_cvt_pk_bf16_f32 v36, v20, v21
	v_cvt_pk_bf16_f32 v37, v22, v23
	v_cvt_pk_bf16_f32 v28, v12, v13
	v_cvt_pk_bf16_f32 v29, v14, v15
	global_load_dwordx4 v[80:83], v[104:105], off offset:2624
	global_load_dwordx4 v[12:15], v[106:107], off offset:2560
	global_load_dwordx4 v[20:23], v[106:107], off offset:2624
	global_load_dwordx4 v[72:75], v[108:109], off offset:2560
	global_load_dwordx4 v[32:35], v[108:109], off offset:2624
	global_load_dwordx4 v[64:67], v[110:111], off offset:2560
	global_load_dwordx4 v[24:27], v[110:111], off offset:2624
	v_cvt_pk_bf16_f32 v45, v30, v31
	v_cvt_pk_bf16_f32 v30, v8, v9
	v_cndmask_b32_e64 v8, 0, 1, s[54:55]
	v_cndmask_b32_e64 v9, 0, 1, s[44:45]
	v_cndmask_b32_e64 v8, v9, v8, s[6:7]
	v_and_b32_e32 v8, 1, v8
	v_cmp_eq_u32_e32 vcc, 1, v8
	v_cndmask_b32_e64 v8, 0, 1, s[46:47]
	v_cndmask_b32_e64 v9, 0, 1, s[48:49]
	v_cndmask_b32_e64 v8, v9, v8, s[6:7]
	v_and_b32_e32 v8, 1, v8
	v_cndmask_b32_e32 v89, 0, v229, vcc
	v_cmp_eq_u32_e32 vcc, 1, v8
	v_cvt_pk_bf16_f32 v54, v58, v59
	v_cvt_pk_bf16_f32 v58, v40, v41
	v_cndmask_b32_e32 v8, 0, v229, vcc
	v_perm_b32 v40, v8, v89, s3
	v_cndmask_b32_e64 v8, 0, 1, s[14:15]
	v_cndmask_b32_e64 v9, 0, 1, s[20:21]
	v_cvt_pk_bf16_f32 v62, v38, v39
	v_cvt_pk_bf16_f32 v38, v16, v17
	v_cndmask_b32_e64 v8, v9, v8, s[6:7]
	v_cndmask_b32_e64 v9, 0, 1, s[28:29]
	v_cndmask_b32_e64 v16, 0, 1, s[30:31]
	v_and_b32_e32 v8, 1, v8
	v_cndmask_b32_e64 v9, v16, v9, s[6:7]
	v_cmp_eq_u32_e32 vcc, 1, v8
	v_and_b32_e32 v9, 1, v9
	s_xor_b64 s[0:1], s[6:7], -1
	v_cndmask_b32_e32 v8, 0, v229, vcc
	v_cmp_eq_u32_e32 vcc, 1, v9
	s_and_b64 s[4:5], s[6:7], exec
	s_cselect_b32 s4, 0x3f80, 0
	v_cndmask_b32_e32 v9, 0, v229, vcc
	v_perm_b32 v41, v9, v8, s3
	v_cndmask_b32_e64 v8, 0, 1, s[94:95]
	v_cndmask_b32_e64 v9, 0, 1, s[96:97]
	s_pack_ll_b32_b16 s16, s4, s4
	v_cndmask_b32_e64 v8, v9, v8, s[6:7]
	v_cvt_pk_bf16_f32 v59, v42, v43
	v_mov_b32_e32 v42, s16
	v_mov_b32_e32 v43, s16
	v_and_b32_e32 v8, 1, v8
	v_cmp_eq_u32_e32 vcc, 1, v8
	s_mov_b32 s18, s16
	s_mov_b32 s19, s16
	v_cndmask_b32_e32 v8, 0, v229, vcc
	v_cvt_pk_bf16_f32 v77, v70, v71
	v_cvt_pk_bf16_f32 v70, v84, v85
	v_cvt_pk_bf16_f32 v71, v86, v87
	s_waitcnt lgkmcnt(0)
	v_cvt_pk_bf16_f32 v53, v56, v57
	v_cvt_pk_bf16_f32 v57, v50, v51
	v_perm_b32 v50, v8, v89, s3
	v_cndmask_b32_e64 v8, 0, 1, s[22:23]
	v_cndmask_b32_e64 v9, 0, 1, s[26:27]
	s_mov_b32 s17, s16
	v_mov_b64_e32 v[86:87], s[18:19]
	v_cndmask_b32_e64 v8, v9, v8, s[6:7]
	v_cndmask_b32_e64 v9, 0, 1, s[10:11]
	v_cndmask_b32_e64 v16, 0, 1, s[68:69]
	v_mov_b64_e32 v[84:85], s[16:17]
	v_cvt_pk_bf16_f32 v39, v18, v19
	v_cndmask_b32_e64 v9, v16, v9, s[6:7]
	v_mfma_f32_16x16x32_bf16 v[16:19], v[40:43], v[76:79], 0
	v_and_b32_e32 v8, 1, v8
	v_cmp_eq_u32_e32 vcc, 1, v8
	v_and_b32_e32 v9, 1, v9
	s_cselect_b32 s4, 0, 0x3f80
	v_cndmask_b32_e32 v8, 0, v229, vcc
	v_cmp_eq_u32_e32 vcc, 1, v9
	s_pack_ll_b32_b16 s4, s4, s4
	v_mfma_f32_16x16x32_bf16 v[16:19], v[84:87], v[68:71], v[16:19]
	v_cndmask_b32_e32 v9, 0, v229, vcc
	v_cvt_pk_bf16_f32 v56, v48, v49
	v_perm_b32 v51, v9, v8, s3
	v_mov_b32_e32 v48, s4
	v_mov_b32_e32 v49, s4
	s_nop 2
	v_mul_f32_e32 v8, 0x3fb8aa3b, v16
	v_mul_f32_e32 v16, 0x3fb8aa3b, v18
	v_mul_f32_e32 v9, 0x3fb8aa3b, v17
	v_exp_f32_e32 v132, v16
	v_mul_f32_e32 v16, 0x3fb8aa3b, v19
	s_waitcnt vmcnt(7)
	v_mfma_f32_16x16x32_bf16 v[128:131], v[124:127], v[0:3], 0
	v_exp_f32_e32 v8, v8
	v_exp_f32_e32 v9, v9
	v_exp_f32_e32 v133, v16
	v_mfma_f32_16x16x32_bf16 v[16:19], v[48:51], v[76:79], 0
	v_cvt_pk_bf16_f32 v31, v10, v11
	ds_write_b128 v134, v[76:79]
	ds_write_b128 v134, v[68:71] offset:1024
	ds_write_b128 v134, v[60:63] offset:2048
	ds_write_b128 v134, v[52:55] offset:3072
	ds_write_b128 v134, v[56:59] offset:4096
	ds_write_b128 v134, v[44:47] offset:5120
	ds_write_b128 v134, v[36:39] offset:6144
	ds_write_b128 v134, v[28:31] offset:7168
	s_nop 2
	v_pk_mul_f32 v[128:129], v[128:129], v[8:9]
	v_pk_mul_f32 v[130:131], v[130:131], v[132:133]
	v_mfma_f32_16x16x32_bf16 v[8:11], v[84:87], v[68:71], v[16:19]
	s_nop 7
	v_mul_f32_e32 v8, 0x3fb8aa3b, v8
	v_exp_f32_e32 v16, v8
	v_mul_f32_e32 v8, 0x3fb8aa3b, v9
	v_exp_f32_e32 v17, v8
	v_mul_f32_e32 v8, 0x3fb8aa3b, v10
	v_exp_f32_e32 v18, v8
	v_mul_f32_e32 v8, 0x3fb8aa3b, v11
	v_exp_f32_e32 v19, v8
	s_waitcnt vmcnt(5)
; __device__ __forceinline__ f32x4 mfma16(bf16x8 a, bf16x8 b, f32x4 c) { return __builtin_amdgcn_mfma_f32_16x16x32_bf16(a, b, c, 0, 0, 0); }
; template <int MODE> __device__ void mixer_gla(const Params& p, int l, int n, LAS unsigned char* lds) {
;     ...
;             for (int ks = 0; ks < 2; ++ks) {
;                 bf16x8 mk[2][2];
; #pragma unroll
;                 for (int t2 = 0; t2 < 2; ++t2)
; #pragma unroll
;                     for (int k2 = 0; k2 < 2; ++k2)
; #pragma unroll
;                         for (int jj = 0; jj < 8; ++jj) { const int tp = 16 * (2 * ks + t2) + c, sidx = SLOT(k2, q, jj); const bool on = dir == 0 ? sidx > tp : sidx < tp; mk[t2][k2][jj] = on ? (short)0x3F80 : (short)0; }
; #pragma unroll
;                 for (int ef = 0; ef < 4; ++ef) { f32x4 kd2[2];
; #pragma unroll
;                     for (int t2 = 0; t2 < 2; ++t2) { const int tj = 2 * ks + t2;
;                         f32x4 E = mfma16(mk[t2][0], laop[ef][0], zero4); E = mfma16(mk[t2][1], laop[ef][1], E);
;                         const f32x4 kR = mfma16(kn[tj][ef >> 1], ident[ef & 1], zero4);
; #pragma unroll
;                         for (int r = 0; r < 4; ++r) kd2[t2][r] = kR[r] * __expf(E[r]); }
;                     kdop[ef][ks] = pack8(kd2[0], kd2[1]); __builtin_amdgcn_sched_barrier(0); }
	v_mfma_f32_16x16x32_bf16 v[8:11], v[12:15], v[0:3], 0
	s_nop 7
	v_pk_mul_f32 v[16:17], v[8:9], v[16:17]
	v_pk_mul_f32 v[18:19], v[10:11], v[18:19]
	v_cvt_pk_bf16_f32 v8, v128, v129
	v_cvt_pk_bf16_f32 v9, v130, v131
	v_cvt_pk_bf16_f32 v10, v16, v17
	v_cvt_pk_bf16_f32 v11, v18, v19
	v_mfma_f32_16x16x32_bf16 v[16:19], v[40:43], v[60:63], 0
	v_mfma_f32_16x16x32_bf16 v[16:19], v[84:87], v[52:55], v[16:19]
	v_mfma_f32_16x16x32_bf16 v[124:127], v[124:127], v[4:7], 0
	v_mfma_f32_16x16x32_bf16 v[12:15], v[12:15], v[4:7], 0
	s_nop 5
	v_mul_f32_e32 v16, 0x3fb8aa3b, v16
	v_mul_f32_e32 v17, 0x3fb8aa3b, v17
	v_exp_f32_e32 v16, v16
	v_exp_f32_e32 v17, v17
	s_nop 0
	v_pk_mul_f32 v[124:125], v[124:125], v[16:17]
	v_mul_f32_e32 v16, 0x3fb8aa3b, v18
	v_mul_f32_e32 v17, 0x3fb8aa3b, v19
	v_exp_f32_e32 v16, v16
	v_exp_f32_e32 v17, v17
	s_nop 0
	v_pk_mul_f32 v[126:127], v[126:127], v[16:17]
	v_mfma_f32_16x16x32_bf16 v[16:19], v[48:51], v[60:63], 0
	v_mfma_f32_16x16x32_bf16 v[16:19], v[84:87], v[52:55], v[16:19]
	s_nop 7
	v_mul_f32_e32 v16, 0x3fb8aa3b, v16
	v_mul_f32_e32 v17, 0x3fb8aa3b, v17
	v_exp_f32_e32 v16, v16
	v_exp_f32_e32 v17, v17
	s_nop 0
	v_pk_mul_f32 v[16:17], v[12:13], v[16:17]
	v_mul_f32_e32 v12, 0x3fb8aa3b, v18
	v_mul_f32_e32 v13, 0x3fb8aa3b, v19
	v_exp_f32_e32 v12, v12
	v_exp_f32_e32 v13, v13
	s_nop 0
	v_pk_mul_f32 v[18:19], v[14:15], v[12:13]
	v_cvt_pk_bf16_f32 v12, v124, v125
	v_cvt_pk_bf16_f32 v13, v126, v127
	v_cvt_pk_bf16_f32 v14, v16, v17
	v_cvt_pk_bf16_f32 v15, v18, v19
	v_mfma_f32_16x16x32_bf16 v[16:19], v[40:43], v[56:59], 0
	v_mfma_f32_16x16x32_bf16 v[16:19], v[84:87], v[44:47], v[16:19]
	v_mfma_f32_16x16x32_bf16 v[124:127], v[80:83], v[0:3], 0
	s_nop 6
	v_mul_f32_e32 v16, 0x3fb8aa3b, v16
	v_mul_f32_e32 v17, 0x3fb8aa3b, v17
	v_exp_f32_e32 v128, v16
	v_mul_f32_e32 v16, 0x3fb8aa3b, v18
	v_exp_f32_e32 v129, v17
	v_exp_f32_e32 v130, v16
	v_mul_f32_e32 v123, 0x3fb8aa3b, v19
	v_mfma_f32_16x16x32_bf16 v[16:19], v[48:51], v[56:59], 0
	v_exp_f32_e32 v131, v123
	v_pk_mul_f32 v[124:125], v[124:125], v[128:129]
	v_pk_mul_f32 v[126:127], v[126:127], v[130:131]
	v_mfma_f32_16x16x32_bf16 v[16:19], v[84:87], v[44:47], v[16:19]
	s_nop 7
	v_mul_f32_e32 v16, 0x3fb8aa3b, v16
	v_exp_f32_e32 v128, v16
	v_mul_f32_e32 v16, 0x3fb8aa3b, v17
	v_exp_f32_e32 v129, v16
	v_mul_f32_e32 v16, 0x3fb8aa3b, v18
	v_exp_f32_e32 v130, v16
	v_mul_f32_e32 v16, 0x3fb8aa3b, v19
	v_exp_f32_e32 v131, v16
	s_waitcnt vmcnt(4)
	v_mfma_f32_16x16x32_bf16 v[16:19], v[20:23], v[0:3], 0
	s_nop 7
	v_pk_mul_f32 v[128:129], v[16:17], v[128:129]
	v_pk_mul_f32 v[130:131], v[18:19], v[130:131]
	v_cvt_pk_bf16_f32 v16, v124, v125
	v_cvt_pk_bf16_f32 v17, v126, v127
	v_cvt_pk_bf16_f32 v18, v128, v129
	v_cvt_pk_bf16_f32 v19, v130, v131
	v_mfma_f32_16x16x32_bf16 v[124:127], v[40:43], v[36:39], 0
	v_mfma_f32_16x16x32_bf16 v[124:127], v[84:87], v[28:31], v[124:127]
	v_mfma_f32_16x16x32_bf16 v[80:83], v[80:83], v[4:7], 0
	v_mfma_f32_16x16x32_bf16 v[20:23], v[20:23], v[4:7], 0
	s_nop 5
	v_mul_f32_e32 v40, 0x3fb8aa3b, v124
	v_mul_f32_e32 v41, 0x3fb8aa3b, v125
	v_exp_f32_e32 v40, v40
	v_exp_f32_e32 v41, v41
	v_mul_f32_e32 v43, 0x3fb8aa3b, v126
	v_pk_mul_f32 v[40:41], v[80:81], v[40:41]
	v_exp_f32_e32 v80, v43
	v_mul_f32_e32 v43, 0x3fb8aa3b, v127
	v_exp_f32_e32 v81, v43
	s_nop 0
	v_pk_mul_f32 v[124:125], v[82:83], v[80:81]
	v_mfma_f32_16x16x32_bf16 v[80:83], v[48:51], v[36:39], 0
	v_mfma_f32_16x16x32_bf16 v[80:83], v[84:87], v[28:31], v[80:83]
	s_nop 7
	v_mul_f32_e32 v43, 0x3fb8aa3b, v80
	v_exp_f32_e32 v50, v43
	v_mul_f32_e32 v43, 0x3fb8aa3b, v81
	v_exp_f32_e32 v51, v43
	s_nop 0
	v_pk_mul_f32 v[50:51], v[20:21], v[50:51]
	v_mul_f32_e32 v20, 0x3fb8aa3b, v82
	v_mul_f32_e32 v21, 0x3fb8aa3b, v83
	v_exp_f32_e32 v20, v20
	v_exp_f32_e32 v21, v21
	s_nop 0
	v_pk_mul_f32 v[80:81], v[22:23], v[20:21]
	v_cvt_pk_bf16_f32 v20, v40, v41
	v_cvt_pk_bf16_f32 v21, v124, v125
	v_cvt_pk_bf16_f32 v22, v50, v51
	v_cvt_pk_bf16_f32 v23, v80, v81
	v_cndmask_b32_e64 v40, 0, 1, s[70:71]
	v_cndmask_b32_e64 v41, 0, 1, s[72:73]
	v_cndmask_b32_e64 v40, v41, v40, s[6:7]
	v_cndmask_b32_e64 v41, 0, 1, s[74:75]
	v_cndmask_b32_e64 v43, 0, 1, s[76:77]
	v_and_b32_e32 v40, 1, v40
	v_cndmask_b32_e64 v41, v43, v41, s[6:7]
	v_cndmask_b32_e64 v43, 0, 1, s[78:79]
	v_cndmask_b32_e64 v49, 0, 1, s[80:81]
	v_cmp_eq_u32_e32 vcc, 1, v40
	v_and_b32_e32 v41, 1, v41
	v_cndmask_b32_e64 v43, v49, v43, s[6:7]
	v_cndmask_b32_e64 v49, 0, 1, s[82:83]
	v_cndmask_b32_e64 v50, 0, 1, s[84:85]
	v_cndmask_b32_e32 v40, 0, v229, vcc
	v_cmp_eq_u32_e32 vcc, 1, v41
	v_and_b32_e32 v43, 1, v43
	v_cndmask_b32_e64 v49, v50, v49, s[6:7]
	v_cndmask_b32_e32 v41, 0, v229, vcc
	v_cmp_eq_u32_e32 vcc, 1, v43
	v_and_b32_e32 v49, 1, v49
	v_cndmask_b32_e64 v51, 0, 1, s[88:89]
	v_cndmask_b32_e32 v43, 0, v229, vcc
	v_cmp_eq_u32_e32 vcc, 1, v49
	v_cndmask_b32_e64 v80, 0, 1, s[92:93]
	s_mov_b32 s5, s4
	v_cndmask_b32_e32 v49, 0, v229, vcc
	v_perm_b32 v50, v49, v89, s3
	v_cndmask_b32_e64 v49, 0, 1, s[86:87]
	v_cndmask_b32_e64 v49, v51, v49, s[6:7]
	v_cndmask_b32_e64 v51, 0, 1, s[90:91]
	v_cndmask_b32_e64 v51, v80, v51, s[6:7]
	s_mov_b32 s6, s4
	s_mov_b32 s7, s4
	v_mov_b64_e32 v[82:83], s[6:7]
	v_and_b32_e32 v49, 1, v49
	v_mov_b64_e32 v[80:81], s[4:5]
	v_cmp_eq_u32_e32 vcc, 1, v49
	v_and_b32_e32 v51, 1, v51
	v_perm_b32 v40, v40, v89, s3
	v_cndmask_b32_e32 v49, 0, v229, vcc
	v_cmp_eq_u32_e32 vcc, 1, v51
	v_perm_b32 v41, v43, v41, s3
	v_mov_b32_e32 v43, s16
	v_cndmask_b32_e32 v51, 0, v229, vcc
	v_perm_b32 v51, v51, v49, s3
	v_mov_b32_e32 v49, s4
	v_mfma_f32_16x16x32_bf16 v[76:79], v[80:83], v[76:79], 0
	v_mfma_f32_16x16x32_bf16 v[84:87], v[40:43], v[68:71], v[76:79]
	v_mfma_f32_16x16x32_bf16 v[68:71], v[48:51], v[68:71], v[76:79]
	s_waitcnt vmcnt(1)
; #define LAS __attribute__((address_space(3)))
; __device__ __forceinline__ unsigned cvtpk(float lo, float hi) { const f32x2 v = (f32x2){lo, hi}; const bf16v2 b = __builtin_convertvector(v, bf16v2); return __builtin_bit_cast(unsigned, b); }
; __device__ __forceinline__ f32x4 mfma16(bf16x8 a, bf16x8 b, f32x4 c) { return __builtin_amdgcn_mfma_f32_16x16x32_bf16(a, b, c, 0, 0, 0); }
; template <int MODE> __device__ void mixer_gla(const Params& p, int l, int n, LAS unsigned char* lds) {
;     ...
;                 for (int ef = 0; ef < 4; ++ef) { f32x4 kd2[2];
; #pragma unroll
;                     for (int t2 = 0; t2 < 2; ++t2) { const int tj = 2 * ks + t2;
;                         f32x4 E = mfma16(mk[t2][0], laop[ef][0], zero4); E = mfma16(mk[t2][1], laop[ef][1], E);
;                         const f32x4 kR = mfma16(kn[tj][ef >> 1], ident[ef & 1], zero4);
; #pragma unroll
;                         for (int r = 0; r < 4; ++r) kd2[t2][r] = kR[r] * __expf(E[r]); }
;                     kdop[ef][ks] = pack8(kd2[0], kd2[1]); __builtin_amdgcn_sched_barrier(0); }
;             }
;             bf16_t* U = uT + ((size_t)(dir * NCH + n) * 4 + h) * 8192 + (size_t)(64 * vh) * 64;
; #pragma unroll
;             for (int vf = 0; vf < 4; ++vf) { bf16x8 vtf[2];
; #pragma unroll
;                 for (int ks = 0; ks < 2; ++ks) { const u32x2 v0 = *(const LAS u32x2*)(VTw + (16 * vf + c) * 72 + 32 * ks + 4 * q), v1 = *(const LAS u32x2*)(VTw + (16 * vf + c) * 72 + 32 * ks + 16 + 4 * q);
;                     vtf[ks] = __builtin_bit_cast(bf16x8, (u32x4){v0.x, v0.y, v1.x, v1.y}); }
; #pragma unroll
;                 for (int ef = 0; ef < 4; ++ef) { f32x4 u = mfma16(kdop[ef][0], vtf[0], zero4); u = mfma16(kdop[ef][1], vtf[1], u);
;                     *(u32x2*)(U + (16 * vf + c) * 64 + 32 * (ef >> 1) + 8 * q + 4 * (ef & 1)) = (u32x2){cvtpk(u[0], u[1]), cvtpk(u[2], u[3])}; } }
	v_mfma_f32_16x16x32_bf16 v[76:79], v[64:67], v[0:3], 0
	s_nop 4
	v_mul_f32_e32 v84, 0x3fb8aa3b, v84
	v_mul_f32_e32 v68, 0x3fb8aa3b, v68
	v_mul_f32_e32 v69, 0x3fb8aa3b, v69
	v_exp_f32_e32 v68, v68
	v_exp_f32_e32 v69, v69
	v_mul_f32_e32 v85, 0x3fb8aa3b, v85
	v_mul_f32_e32 v86, 0x3fb8aa3b, v86
	v_mul_f32_e32 v87, 0x3fb8aa3b, v87
	v_pk_mul_f32 v[76:77], v[76:77], v[68:69]
	v_mul_f32_e32 v68, 0x3fb8aa3b, v70
	v_mul_f32_e32 v69, 0x3fb8aa3b, v71
	v_mfma_f32_16x16x32_bf16 v[124:127], v[72:75], v[0:3], 0
	v_exp_f32_e32 v84, v84
	v_exp_f32_e32 v85, v85
	v_exp_f32_e32 v86, v86
	v_exp_f32_e32 v87, v87
	v_exp_f32_e32 v68, v68
	v_exp_f32_e32 v69, v69
	s_nop 1
	v_pk_mul_f32 v[84:85], v[124:125], v[84:85]
	v_pk_mul_f32 v[86:87], v[126:127], v[86:87]
	v_cvt_pk_bf16_f32 v70, v76, v77
	v_pk_mul_f32 v[78:79], v[78:79], v[68:69]
	v_cvt_pk_bf16_f32 v68, v84, v85
	v_cvt_pk_bf16_f32 v69, v86, v87
	v_cvt_pk_bf16_f32 v71, v78, v79
	v_mfma_f32_16x16x32_bf16 v[60:63], v[80:83], v[60:63], 0
	v_mfma_f32_16x16x32_bf16 v[76:79], v[40:43], v[52:55], v[60:63]
	v_mfma_f32_16x16x32_bf16 v[52:55], v[48:51], v[52:55], v[60:63]
	v_mfma_f32_16x16x32_bf16 v[72:75], v[72:75], v[4:7], 0
	s_nop 5
	v_mul_f32_e32 v76, 0x3fb8aa3b, v76
	v_mul_f32_e32 v52, 0x3fb8aa3b, v52
	v_exp_f32_e32 v60, v52
	v_mul_f32_e32 v52, 0x3fb8aa3b, v53
	v_exp_f32_e32 v61, v52
	v_mul_f32_e32 v52, 0x3fb8aa3b, v54
	v_mul_f32_e32 v77, 0x3fb8aa3b, v77
	v_mul_f32_e32 v78, 0x3fb8aa3b, v78
	v_mul_f32_e32 v79, 0x3fb8aa3b, v79
	v_exp_f32_e32 v62, v52
	v_mul_f32_e32 v52, 0x3fb8aa3b, v55
	v_exp_f32_e32 v76, v76
	v_exp_f32_e32 v77, v77
	v_exp_f32_e32 v78, v78
	v_exp_f32_e32 v79, v79
	v_exp_f32_e32 v63, v52
	v_mfma_f32_16x16x32_bf16 v[52:55], v[64:67], v[4:7], 0
	v_mul_f32_e64 v72, v72, v76
	v_mul_f32_e64 v73, v73, v77
	v_pk_mul_f32 v[74:75], v[74:75], v[78:79]
	s_nop 4
	v_pk_mul_f32 v[60:61], v[52:53], v[60:61]
	v_pk_mul_f32 v[62:63], v[54:55], v[62:63]
	v_cvt_pk_bf16_f32 v52, v72, v73
	v_cvt_pk_bf16_f32 v53, v74, v75
	v_cvt_pk_bf16_f32 v54, v60, v61
	v_cvt_pk_bf16_f32 v55, v62, v63
	v_mfma_f32_16x16x32_bf16 v[56:59], v[80:83], v[56:59], 0
	v_mfma_f32_16x16x32_bf16 v[60:63], v[40:43], v[44:47], v[56:59]
	v_mfma_f32_16x16x32_bf16 v[44:47], v[48:51], v[44:47], v[56:59]
	s_nop 6
	v_mul_f32_e32 v60, 0x3fb8aa3b, v60
	v_mul_f32_e32 v44, 0x3fb8aa3b, v44
	v_exp_f32_e32 v56, v44
	v_mul_f32_e32 v44, 0x3fb8aa3b, v45
	v_exp_f32_e32 v57, v44
	v_mul_f32_e32 v44, 0x3fb8aa3b, v46
	v_mul_f32_e32 v61, 0x3fb8aa3b, v61
	v_mul_f32_e32 v62, 0x3fb8aa3b, v62
	v_mul_f32_e32 v67, 0x3fb8aa3b, v63
	v_exp_f32_e32 v58, v44
	v_mul_f32_e32 v44, 0x3fb8aa3b, v47
	v_exp_f32_e32 v64, v60
	v_exp_f32_e32 v65, v61
	v_exp_f32_e32 v66, v62
	v_mfma_f32_16x16x32_bf16 v[60:63], v[32:35], v[0:3], 0
	v_exp_f32_e32 v67, v67
	v_exp_f32_e32 v59, v44
	s_waitcnt vmcnt(0)
	v_mfma_f32_16x16x32_bf16 v[44:47], v[24:27], v[0:3], 0
	s_nop 3
	v_mul_f32_e64 v60, v60, v64
	v_mul_f32_e64 v61, v61, v65
	v_pk_mul_f32 v[62:63], v[62:63], v[66:67]
	s_nop 0
	v_pk_mul_f32 v[56:57], v[44:45], v[56:57]
	v_pk_mul_f32 v[58:59], v[46:47], v[58:59]
	v_cvt_pk_bf16_f32 v44, v60, v61
	v_cvt_pk_bf16_f32 v45, v62, v63
	v_cvt_pk_bf16_f32 v46, v56, v57
	v_cvt_pk_bf16_f32 v47, v58, v59
	v_mfma_f32_16x16x32_bf16 v[36:39], v[80:83], v[36:39], 0
	v_mfma_f32_16x16x32_bf16 v[40:43], v[40:43], v[28:31], v[36:39]
	v_mfma_f32_16x16x32_bf16 v[28:31], v[48:51], v[28:31], v[36:39]
	v_mfma_f32_16x16x32_bf16 v[32:35], v[32:35], v[4:7], 0
	s_nop 5
	v_mul_f32_e32 v40, 0x3fb8aa3b, v40
	v_mul_f32_e32 v41, 0x3fb8aa3b, v41
	v_mul_f32_e32 v42, 0x3fb8aa3b, v42
	v_mul_f32_e32 v43, 0x3fb8aa3b, v43
	v_mul_f32_e32 v28, 0x3fb8aa3b, v28
	v_mul_f32_e32 v29, 0x3fb8aa3b, v29
	v_mul_f32_e32 v30, 0x3fb8aa3b, v30
	v_mul_f32_e32 v31, 0x3fb8aa3b, v31
	v_exp_f32_e32 v40, v40
	v_exp_f32_e32 v41, v41
	v_exp_f32_e32 v42, v42
	v_exp_f32_e32 v43, v43
	v_exp_f32_e32 v28, v28
	v_exp_f32_e32 v29, v29
	v_exp_f32_e32 v30, v30
	v_exp_f32_e32 v31, v31
	v_mfma_f32_16x16x32_bf16 v[24:27], v[24:27], v[4:7], 0
	v_mul_f32_e64 v32, v32, v40
	v_mul_f32_e64 v33, v33, v41
	v_pk_mul_f32 v[34:35], v[34:35], v[42:43]
	s_nop 4
	v_pk_mul_f32 v[28:29], v[24:25], v[28:29]
	v_pk_mul_f32 v[30:31], v[26:27], v[30:31]
	v_cvt_pk_bf16_f32 v24, v32, v33
	v_cvt_pk_bf16_f32 v25, v34, v35
	v_cvt_pk_bf16_f32 v26, v28, v29
	v_cvt_pk_bf16_f32 v27, v30, v31
	ds_read2_b64 v[28:31], v120 offset1:4
	ds_read2_b64 v[32:35], v120 offset0:8 offset1:12
	s_lshl_b64 s[4:5], s[8:9], 16
	v_lshl_add_u64 v[48:49], v[112:113], 0, s[4:5]
	s_movk_i32 s4, 0x1000
	s_waitcnt lgkmcnt(1)
; #define LAS __attribute__((address_space(3)))
; __device__ __forceinline__ unsigned cvtpk(float lo, float hi) { const f32x2 v = (f32x2){lo, hi}; const bf16v2 b = __builtin_convertvector(v, bf16v2); return __builtin_bit_cast(unsigned, b); }
; __device__ __forceinline__ f32x4 mfma16(bf16x8 a, bf16x8 b, f32x4 c) { return __builtin_amdgcn_mfma_f32_16x16x32_bf16(a, b, c, 0, 0, 0); }
; template <int MODE> __device__ void mixer_gla(const Params& p, int l, int n, LAS unsigned char* lds) {
;     ...
;             bf16_t* U = uT + ((size_t)(dir * NCH + n) * 4 + h) * 8192 + (size_t)(64 * vh) * 64;
; #pragma unroll
;             for (int vf = 0; vf < 4; ++vf) { bf16x8 vtf[2];
; #pragma unroll
;                 for (int ks = 0; ks < 2; ++ks) { const u32x2 v0 = *(const LAS u32x2*)(VTw + (16 * vf + c) * 72 + 32 * ks + 4 * q), v1 = *(const LAS u32x2*)(VTw + (16 * vf + c) * 72 + 32 * ks + 16 + 4 * q);
;                     vtf[ks] = __builtin_bit_cast(bf16x8, (u32x4){v0.x, v0.y, v1.x, v1.y}); }
; #pragma unroll
;                 for (int ef = 0; ef < 4; ++ef) { f32x4 u = mfma16(kdop[ef][0], vtf[0], zero4); u = mfma16(kdop[ef][1], vtf[1], u);
;                     *(u32x2*)(U + (16 * vf + c) * 64 + 32 * (ef >> 1) + 8 * q + 4 * (ef & 1)) = (u32x2){cvtpk(u[0], u[1]), cvtpk(u[2], u[3])}; } }
	v_mfma_f32_16x16x32_bf16 v[36:39], v[8:11], v[28:31], 0
	s_mov_b32 s5, 1
	s_mov_b64 s[6:7], 0
	s_waitcnt lgkmcnt(0)
	v_mfma_f32_16x16x32_bf16 v[36:39], v[68:71], v[32:35], v[36:39]
	s_nop 7
	v_cvt_pk_bf16_f32 v36, v36, v37
	v_cvt_pk_bf16_f32 v37, v38, v39
	v_mfma_f32_16x16x32_bf16 v[38:41], v[12:15], v[28:31], 0
	v_mfma_f32_16x16x32_bf16 v[38:41], v[52:55], v[32:35], v[38:41]
	s_nop 7
	v_cvt_pk_bf16_f32 v38, v38, v39
	v_cvt_pk_bf16_f32 v39, v40, v41
	global_store_dwordx4 v[48:49], v[36:39], off
	s_nop 1
	v_mfma_f32_16x16x32_bf16 v[36:39], v[16:19], v[28:31], 0
	v_mfma_f32_16x16x32_bf16 v[28:31], v[20:23], v[28:31], 0
	v_mfma_f32_16x16x32_bf16 v[36:39], v[44:47], v[32:35], v[36:39]
	v_mfma_f32_16x16x32_bf16 v[28:31], v[24:27], v[32:35], v[28:31]
	s_nop 6
	v_cvt_pk_bf16_f32 v36, v36, v37
	v_cvt_pk_bf16_f32 v37, v38, v39
	v_cvt_pk_bf16_f32 v38, v28, v29
	v_cvt_pk_bf16_f32 v39, v30, v31
	global_store_dwordx4 v[48:49], v[36:39], off offset:64
	ds_read2_b64 v[28:31], v121 offset1:4
	ds_read2_b64 v[32:35], v121 offset0:8 offset1:12
	s_waitcnt lgkmcnt(1)
	v_mfma_f32_16x16x32_bf16 v[36:39], v[8:11], v[28:31], 0
	s_waitcnt lgkmcnt(0)
	v_mfma_f32_16x16x32_bf16 v[36:39], v[68:71], v[32:35], v[36:39]
	s_nop 7
	v_cvt_pk_bf16_f32 v36, v36, v37
	v_cvt_pk_bf16_f32 v37, v38, v39
	v_mfma_f32_16x16x32_bf16 v[38:41], v[12:15], v[28:31], 0
	v_mfma_f32_16x16x32_bf16 v[38:41], v[52:55], v[32:35], v[38:41]
	s_nop 7
	v_cvt_pk_bf16_f32 v38, v38, v39
	v_cvt_pk_bf16_f32 v39, v40, v41
	global_store_dwordx4 v[48:49], v[36:39], off offset:2048
	s_nop 1
	v_mfma_f32_16x16x32_bf16 v[36:39], v[16:19], v[28:31], 0
	v_mfma_f32_16x16x32_bf16 v[28:31], v[20:23], v[28:31], 0
	v_mfma_f32_16x16x32_bf16 v[36:39], v[44:47], v[32:35], v[36:39]
	v_mfma_f32_16x16x32_bf16 v[28:31], v[24:27], v[32:35], v[28:31]
	s_nop 6
	v_cvt_pk_bf16_f32 v36, v36, v37
	v_cvt_pk_bf16_f32 v37, v38, v39
	v_cvt_pk_bf16_f32 v38, v28, v29
	v_cvt_pk_bf16_f32 v39, v30, v31
	global_store_dwordx4 v[48:49], v[36:39], off offset:2112
	ds_read2_b64 v[30:33], v122 offset1:4
	ds_read2_b64 v[34:37], v122 offset0:8 offset1:12
	s_waitcnt lgkmcnt(1)
	v_mfma_f32_16x16x32_bf16 v[38:41], v[8:11], v[30:33], 0
	v_add_co_u32_e32 v28, vcc, s4, v48
	s_waitcnt lgkmcnt(0)
	v_mfma_f32_16x16x32_bf16 v[38:41], v[68:71], v[34:37], v[38:41]
	v_addc_co_u32_e32 v29, vcc, 0, v49, vcc
	s_andn2_b64 vcc, exec, s[0:1]
	s_nop 5
	v_cvt_pk_bf16_f32 v38, v38, v39
	v_cvt_pk_bf16_f32 v39, v40, v41
	v_mfma_f32_16x16x32_bf16 v[40:43], v[12:15], v[30:33], 0
	v_mfma_f32_16x16x32_bf16 v[40:43], v[52:55], v[34:37], v[40:43]
	s_nop 7
	v_cvt_pk_bf16_f32 v40, v40, v41
	v_cvt_pk_bf16_f32 v41, v42, v43
	global_store_dwordx4 v[28:29], v[38:41], off
	s_nop 1
	v_mfma_f32_16x16x32_bf16 v[38:41], v[16:19], v[30:33], 0
	v_mfma_f32_16x16x32_bf16 v[30:33], v[20:23], v[30:33], 0
	v_mfma_f32_16x16x32_bf16 v[38:41], v[44:47], v[34:37], v[38:41]
	v_mfma_f32_16x16x32_bf16 v[30:33], v[24:27], v[34:37], v[30:33]
	v_add_u32_e32 v34, 0x1800, v120
	s_nop 5
	v_cvt_pk_bf16_f32 v38, v38, v39
	v_cvt_pk_bf16_f32 v39, v40, v41
	v_cvt_pk_bf16_f32 v40, v30, v31
	v_cvt_pk_bf16_f32 v41, v32, v33
	global_store_dwordx4 v[28:29], v[38:41], off offset:64
	ds_read2_b64 v[30:33], v34 offset0:96 offset1:100
	ds_read2_b64 v[34:37], v34 offset0:104 offset1:108
	s_waitcnt lgkmcnt(1)
	v_mfma_f32_16x16x32_bf16 v[8:11], v[8:11], v[30:33], 0
	s_waitcnt lgkmcnt(0)
	v_mfma_f32_16x16x32_bf16 v[8:11], v[68:71], v[34:37], v[8:11]
	s_nop 7
	v_cvt_pk_bf16_f32 v8, v8, v9
	v_cvt_pk_bf16_f32 v9, v10, v11
	v_mfma_f32_16x16x32_bf16 v[10:13], v[12:15], v[30:33], 0
	v_mfma_f32_16x16x32_bf16 v[10:13], v[52:55], v[34:37], v[10:13]
	s_nop 7
	v_cvt_pk_bf16_f32 v10, v10, v11
	v_cvt_pk_bf16_f32 v11, v12, v13
	global_store_dwordx4 v[28:29], v[8:11], off offset:2048
	s_nop 1
	v_mfma_f32_16x16x32_bf16 v[8:11], v[16:19], v[30:33], 0
	v_mfma_f32_16x16x32_bf16 v[8:11], v[44:47], v[34:37], v[8:11]
	s_nop 7
	v_cvt_pk_bf16_f32 v8, v8, v9
	v_cvt_pk_bf16_f32 v9, v10, v11
	v_mfma_f32_16x16x32_bf16 v[10:13], v[20:23], v[30:33], 0
	v_mfma_f32_16x16x32_bf16 v[10:13], v[24:27], v[34:37], v[10:13]
	s_nop 7
	v_cvt_pk_bf16_f32 v10, v10, v11
	v_cvt_pk_bf16_f32 v11, v12, v13
	global_store_dwordx4 v[28:29], v[8:11], off offset:2112
	s_cbranch_vccz .LBB0_327
